# MLA MFMA-shadow fill: row-max of completed score tiles and m/l copies interleaved between QK MFMAs, m/l copy-back between PV MFMAs
# speedup vs baseline: 1.0288x; 1.0030x over previous
; #define LAS __attribute__((address_space(3)))
; __device__ __forceinline__ float ex2(float x) { return __builtin_amdgcn_exp2f(x); }
; __device__ __forceinline__ f32x4 mfma16(bf16x8 a, bf16x8 b, f32x4 c) { return __builtin_amdgcn_mfma_f32_16x16x32_bf16(a, b, c, 0, 0, 0); }
;   __device__ __forceinline__ bf16_t* W() const { return (bf16_t*)(ws + WS_W); }
; template <int NT, int NKK, int NDT, int MODE, bool MASK> ...
;     ...
;   f32x4 s[NT][4];
;   __builtin_amdgcn_s_setprio(1);
; #pragma unroll
;   for (int t = 0; t < 4; ++t)
; #pragma unroll
;     for (int kk = 0; kk < NKK; ++kk) {
;       const bf16x8 kf = *(LAS const bf16x8*)(Kl + (16 * t + r) * KSTR + (32 * kk + 8 * lg) * 2);
; #pragma unroll
;       for (int j = 0; j < NT; ++j) s[j][t] = mfma16(kf, qf[j][kk], kk == 0 ? (f32x4){0.f, 0.f, 0.f, 0.f} : s[j][t]);
;     }
;   __builtin_amdgcn_s_setprio(0);
;   bf16x8 pf[NT][2];
; #pragma unroll
;   for (int j = 0; j < NT; ++j) {
;     float mx = -INFINITY;
; #pragma unroll
;     for (int t = 0; t < 4; ++t)
; #pragma unroll
;       for (int i = 0; i < 4; ++i) {
;         if (MASK) { const int kp = kpos0 + 16 * t + 4 * lg + i; if (!mask_ok<MODE>(tq[j], kp, W)) s[j][t][i] = -INFINITY; }
;         mx = fmaxf(mx, s[j][t][i]);
;       }
;     mx = max_x16_x32(mx);
;     if (__any(mx > m[j] + 8.0f / c)) {
;       const float mnew = fmaxf(m[j], mx);
;       const float ms2 = (mnew == -INFINITY) ? 0.f : mnew;
;       const float alpha = ex2((m[j] - ms2) * c);
;       m[j] = mnew; l[j] *= alpha;
; #pragma unroll
;       for (int dt = 0; dt < NDT; ++dt) o[j][dt] *= alpha;
;     }
.LBB0_768:
	s_waitcnt lgkmcnt(0)
	s_barrier
	s_add_i32 s8, s69, 0xffffff41
	s_cmp_gt_i32 s8, s68
	s_cbranch_scc1 .LBB0_797
	s_add_i32 s8, s69, 0xffffff80
	s_cmp_gt_i32 s8, s59
	s_setprio 1
	v_add_u32_e32 v1, s71, v236
	s_waitcnt lgkmcnt(0)
	v_add_u32_e32 v94, v1, v237
	ds_read_b128 v[134:137], v94
	ds_read_b128 v[130:133], v94 offset:64
	ds_read_b128 v[126:129], v94 offset:128
	ds_read_b128 v[122:125], v94 offset:3328
	ds_read_b128 v[118:121], v94 offset:3392
	ds_read_b128 v[114:117], v94 offset:3456
	ds_read_b128 v[106:109], v94 offset:6656
	ds_read_b128 v[98:101], v94 offset:6720
	v_add_u32_e32 v201, v1, v238
	ds_read_b128 v[110:113], v94 offset:6784
	ds_read_b128 v[102:105], v201
	ds_read_b128 v[94:97], v201 offset:64
	s_mov_b64 s[20:21], -1
	v_add_f32_e32 v1, 0x4259535f, v220
	s_cbranch_scc1 .LBB0_788
	s_waitcnt lgkmcnt(10)
	v_mfma_f32_16x16x32_bf16 v[138:141], v[134:137], v[18:21], 0
	ds_read_b128 v[146:149], v201 offset:128
	v_mov_b32_e32 v234, 0x260
	v_mfma_f32_16x16x32_bf16 v[142:145], v[134:137], v[10:13], 0
	s_waitcnt lgkmcnt(10)
	v_mfma_f32_16x16x32_bf16 v[138:141], v[130:133], v[2:5], v[138:141]
	v_mov_b64_e32 v[222:223], v[220:221]
	v_mfma_f32_16x16x32_bf16 v[142:145], v[130:133], v[14:17], v[142:145]
	v_mov_b64_e32 v[224:225], v[218:219]
	s_waitcnt lgkmcnt(9)
	v_mfma_f32_16x16x32_bf16 v[182:185], v[126:129], v[6:9], v[138:141]
	v_mfma_f32_16x16x32_bf16 v[166:169], v[126:129], v[22:25], v[142:145]
	v_mov_b32_e32 v187, v220
	s_waitcnt lgkmcnt(8)
	v_mfma_f32_16x16x32_bf16 v[138:141], v[122:125], v[18:21], 0
	v_mfma_f32_16x16x32_bf16 v[142:145], v[122:125], v[10:13], 0
	s_waitcnt lgkmcnt(7)
	v_mfma_f32_16x16x32_bf16 v[138:141], v[118:121], v[2:5], v[138:141]
	v_mfma_f32_16x16x32_bf16 v[142:145], v[118:121], v[14:17], v[142:145]
	s_waitcnt lgkmcnt(6)
	v_mfma_f32_16x16x32_bf16 v[178:181], v[114:117], v[6:9], v[138:141]
	v_mfma_f32_16x16x32_bf16 v[154:157], v[114:117], v[22:25], v[142:145]
	s_waitcnt lgkmcnt(5)
	v_mfma_f32_16x16x32_bf16 v[138:141], v[106:109], v[18:21], 0
	v_mfma_f32_16x16x32_bf16 v[142:145], v[106:109], v[10:13], 0
	v_max3_f32 v188, v182, s81, v183
	s_waitcnt lgkmcnt(4)
	v_mfma_f32_16x16x32_bf16 v[138:141], v[98:101], v[2:5], v[138:141]
	v_max3_f32 v188, v188, v184, v185
	v_mfma_f32_16x16x32_bf16 v[142:145], v[98:101], v[14:17], v[142:145]
	v_max3_f32 v189, v166, s81, v167
	s_waitcnt lgkmcnt(3)
	v_mfma_f32_16x16x32_bf16 v[174:177], v[110:113], v[6:9], v[138:141]
	v_max3_f32 v189, v189, v168, v169
	v_mfma_f32_16x16x32_bf16 v[150:153], v[110:113], v[22:25], v[142:145]
	s_waitcnt lgkmcnt(2)
	v_mfma_f32_16x16x32_bf16 v[138:141], v[102:105], v[18:21], 0
	v_mfma_f32_16x16x32_bf16 v[142:145], v[102:105], v[10:13], 0
	v_max3_f32 v188, v188, v178, v179
	s_waitcnt lgkmcnt(1)
	v_mfma_f32_16x16x32_bf16 v[138:141], v[94:97], v[2:5], v[138:141]
	v_max3_f32 v188, v188, v180, v181
	v_mfma_f32_16x16x32_bf16 v[142:145], v[94:97], v[14:17], v[142:145]
	v_max3_f32 v189, v189, v154, v155
	s_waitcnt lgkmcnt(0)
	v_mfma_f32_16x16x32_bf16 v[170:173], v[146:149], v[6:9], v[138:141]
	v_max3_f32 v189, v189, v156, v157
	v_mfma_f32_16x16x32_bf16 v[142:145], v[146:149], v[22:25], v[142:145]
	s_setprio 0
	s_nop 3
	v_max3_f32 v138, v188, v174, v175
	v_max3_f32 v138, v138, v176, v177
	v_max3_f32 v138, v138, v170, v171
	v_max3_f32 v138, v138, v172, v173
	v_mov_b32_e32 v139, v138
	s_nop 1
	v_permlane16_swap_b32_e32 v138, v139
	v_max_f32_e32 v138, v138, v139
	v_mov_b32_e32 v139, v138
	s_nop 1
	v_permlane32_swap_b32_e32 v138, v139
	v_max_f32_e32 v186, v138, v139
	v_cmp_gt_f32_e32 vcc, v186, v1
	s_cbranch_vccz .LBB0_772
	v_max_f32_e32 v138, v186, v186
	v_max_f32_e32 v139, v220, v220
	v_max_f32_e32 v222, v139, v138
	v_cmp_neq_f32_e32 vcc, s81, v222
	v_mov_b32_e32 v223, v221
	v_mov_b32_e32 v225, v219
	v_cndmask_b32_e32 v138, 0, v222, vcc
	v_sub_f32_e32 v138, v220, v138
	v_mul_f32_e32 v138, 0x3e16c740, v138
	v_exp_f32_e32 v138, v138
	v_mov_b32_e32 v187, v222
	v_mul_f32_e32 v224, v218, v138
	v_pk_mul_f32 v[92:93], v[92:93], v[138:139] op_sel_hi:[1,0]
	v_pk_mul_f32 v[90:91], v[90:91], v[138:139] op_sel_hi:[1,0]
	v_pk_mul_f32 v[88:89], v[88:89], v[138:139] op_sel_hi:[1,0]
	v_pk_mul_f32 v[86:87], v[86:87], v[138:139] op_sel_hi:[1,0]
	v_pk_mul_f32 v[76:77], v[76:77], v[138:139] op_sel_hi:[1,0]
	v_pk_mul_f32 v[74:75], v[74:75], v[138:139] op_sel_hi:[1,0]
	v_pk_mul_f32 v[68:69], v[68:69], v[138:139] op_sel_hi:[1,0]
	v_pk_mul_f32 v[66:67], v[66:67], v[138:139] op_sel_hi:[1,0]
; __device__ __forceinline__ float ex2(float x) { return __builtin_amdgcn_exp2f(x); }
;   __device__ __forceinline__ bf16_t* W() const { return (bf16_t*)(ws + WS_W); }
; template <int NT, int NKK, int NDT, int MODE, bool MASK> ...
;     ...
;   for (int j = 0; j < NT; ++j) {
;     float mx = -INFINITY;
; #pragma unroll
;     for (int t = 0; t < 4; ++t)
; #pragma unroll
;       for (int i = 0; i < 4; ++i) {
;         if (MASK) { const int kp = kpos0 + 16 * t + 4 * lg + i; if (!mask_ok<MODE>(tq[j], kp, W)) s[j][t][i] = -INFINITY; }
;         mx = fmaxf(mx, s[j][t][i]);
;       }
;     mx = max_x16_x32(mx);
;     if (__any(mx > m[j] + 8.0f / c)) {
;       const float mnew = fmaxf(m[j], mx);
;       const float ms2 = (mnew == -INFINITY) ? 0.f : mnew;
;       const float alpha = ex2((m[j] - ms2) * c);
;       m[j] = mnew; l[j] *= alpha;
; #pragma unroll
;       for (int dt = 0; dt < NDT; ++dt) o[j][dt] *= alpha;
;     }
;     const float mc = ((m[j] == -INFINITY) ? 0.f : m[j]) * c;
;     float p[4][4], ps = 0.f;
; #pragma unroll
;     for (int t = 0; t < 4; ++t)
; #pragma unroll
;       for (int i = 0; i < 4; ++i) { p[t][i] = ex2(s[j][t][i] * c - mc); ps += p[t][i]; }
;     l[j] += ps;
.LBB0_772:
	v_mul_f32_e32 v186, 0x3e16c740, v187
	v_cmp_neq_f32_e32 vcc, s81, v187
	s_nop 1
	v_cndmask_b32_e32 v186, 0, v186, vcc
	v_fma_f32 v182, v182, s88, -v186
	v_exp_f32_e32 v205, v182
	v_fma_f32 v182, v183, s88, -v186
	v_exp_f32_e32 v207, v182
	v_fma_f32 v182, v184, s88, -v186
	v_exp_f32_e32 v246, v182
	v_fma_f32 v182, v185, s88, -v186
	v_exp_f32_e32 v247, v182
	v_fma_f32 v178, v178, s88, -v186
	v_exp_f32_e32 v248, v178
	v_fma_f32 v178, v179, s88, -v186
	v_add_f32_e32 v182, v207, v205
	v_exp_f32_e32 v249, v178
	v_fma_f32 v178, v180, s88, -v186
	v_add_f32_e32 v182, v246, v182
	v_exp_f32_e32 v250, v178
	v_fma_f32 v178, v181, s88, -v186
	v_add_f32_e32 v182, v247, v182
	v_exp_f32_e32 v251, v178
	v_fma_f32 v174, v174, s88, -v186
	v_add_f32_e32 v178, v248, v182
	v_exp_f32_e32 v252, v174
	v_fma_f32 v174, v175, s88, -v186
	v_add_f32_e32 v178, v249, v178
	v_exp_f32_e32 v231, v174
	v_fma_f32 v174, v176, s88, -v186
	v_add_f32_e32 v178, v250, v178
	v_exp_f32_e32 v229, v174
	v_fma_f32 v174, v177, s88, -v186
	v_add_f32_e32 v178, v251, v178
	v_exp_f32_e32 v230, v174
	v_fma_f32 v170, v170, s88, -v186
	v_add_f32_e32 v174, v252, v178
	v_exp_f32_e32 v232, v170
	v_fma_f32 v170, v171, s88, -v186
	v_add_f32_e32 v174, v231, v174
	v_exp_f32_e32 v228, v170
	v_fma_f32 v170, v172, s88, -v186
	v_add_f32_e32 v174, v229, v174
	v_exp_f32_e32 v196, v170
	v_fma_f32 v170, v173, s88, -v186
	v_add_f32_e32 v174, v230, v174
	v_exp_f32_e32 v173, v170
	v_add_f32_e32 v170, v232, v174
	v_add_f32_e32 v170, v228, v170
	v_add_f32_e32 v170, v196, v170
	v_add_f32_e32 v170, v173, v170
	v_add_f32_e32 v224, v224, v170
	v_max3_f32 v170, v189, v150, v151
	v_max3_f32 v170, v170, v152, v153
	v_max3_f32 v170, v170, v142, v143
	v_max3_f32 v170, v170, v144, v145
	v_mov_b32_e32 v171, v170
	s_nop 1
	v_permlane16_swap_b32_e32 v170, v171
	v_max_f32_e32 v170, v170, v171
	v_mov_b32_e32 v171, v170
	s_nop 1
	v_permlane32_swap_b32_e32 v170, v171
	v_max_f32_e32 v170, v170, v171
	v_add_f32_e32 v171, 0x4259535f, v223
	v_cmp_gt_f32_e32 vcc, v170, v171
	s_cbranch_vccz .LBB0_786
	v_max_f32_e32 v170, v170, v170
	v_max_f32_e32 v171, v223, v223
	v_max_f32_e32 v197, v171, v170
	v_cmp_neq_f32_e32 vcc, s81, v197
	s_nop 1
	v_cndmask_b32_e32 v170, 0, v197, vcc
	v_sub_f32_e32 v170, v223, v170
	v_mul_f32_e32 v170, 0x3e16c740, v170
	v_exp_f32_e32 v170, v170
	v_mov_b32_e32 v223, v197
	v_mul_f32_e32 v225, v225, v170
	v_pk_mul_f32 v[84:85], v[84:85], v[170:171] op_sel_hi:[1,0]
	v_pk_mul_f32 v[82:83], v[82:83], v[170:171] op_sel_hi:[1,0]
	v_pk_mul_f32 v[80:81], v[80:81], v[170:171] op_sel_hi:[1,0]
	v_pk_mul_f32 v[78:79], v[78:79], v[170:171] op_sel_hi:[1,0]
	v_pk_mul_f32 v[72:73], v[72:73], v[170:171] op_sel_hi:[1,0]
	v_pk_mul_f32 v[70:71], v[70:71], v[170:171] op_sel_hi:[1,0]
	v_pk_mul_f32 v[64:65], v[64:65], v[170:171] op_sel_hi:[1,0]
	v_pk_mul_f32 v[62:63], v[62:63], v[170:171] op_sel_hi:[1,0]
	s_branch .LBB0_787

; __device__ __forceinline__ float ex2(float x) { return __builtin_amdgcn_exp2f(x); }
; __device__ __forceinline__ f32x4 mfma16(bf16x8 a, bf16x8 b, f32x4 c) { return __builtin_amdgcn_mfma_f32_16x16x32_bf16(a, b, c, 0, 0, 0); }
; __device__ __forceinline__ s16x4 ds_tr(LAS const unsigned char* p) { return __builtin_bit_cast(s16x4, __builtin_amdgcn_ds_read_tr16_b64_v4i16((LAS v4i16_t*)p)); }
; template <int NT, int NKK, int NDT, int MODE, bool MASK> ...
;     ...
;     const float mc = ((m[j] == -INFINITY) ? 0.f : m[j]) * c;
;     float p[4][4], ps = 0.f;
; #pragma unroll
;     for (int t = 0; t < 4; ++t)
; #pragma unroll
;       for (int i = 0; i < 4; ++i) { p[t][i] = ex2(s[j][t][i] * c - mc); ps += p[t][i]; }
;     l[j] += ps;
;     pf[j][0] = pack8(p[0], p[1]); pf[j][1] = pack8(p[2], p[3]);
;   }
;   __builtin_amdgcn_s_setprio(1);
; #pragma unroll
;   for (int st = 0; st < 2; ++st)
; #pragma unroll
;     for (int dt = 0; dt < NDT; ++dt) {
;       const s16x4 v0 = ds_tr(Vl + (32 * st + 4 * lg + vq) * VSTR + (16 * dt + 4 * vp) * 2);
;       const s16x4 v1 = ds_tr(Vl + (32 * st + 16 + 4 * lg + vq) * VSTR + (16 * dt + 4 * vp) * 2);
;       const bf16x8 vf = (bf16x8){v0[0], v0[1], v0[2], v0[3], v1[0], v1[1], v1[2], v1[3]};
; #pragma unroll
;       for (int j = 0; j < NT; ++j) o[j][dt] = mfma16(vf, pf[j][st], o[j][dt]);
;     }
;   __builtin_amdgcn_s_setprio(0);
.LBB0_787:
	v_cvt_pk_bf16_f32 v173, v196, v173
	v_mul_f32_e32 v196, 0x3e16c740, v197
	v_cmp_neq_f32_e32 vcc, s81, v197
	v_cvt_pk_bf16_f32 v172, v232, v228
	v_cvt_pk_bf16_f32 v228, v205, v207
	v_cndmask_b32_e32 v196, 0, v196, vcc
	v_fma_f32 v166, v166, s88, -v196
	v_exp_f32_e32 v166, v166
	v_fma_f32 v167, v167, s88, -v196
	v_exp_f32_e32 v167, v167
	v_fma_f32 v168, v168, s88, -v196
	v_exp_f32_e32 v168, v168
	v_fma_f32 v169, v169, s88, -v196
	v_exp_f32_e32 v169, v169
	v_fma_f32 v154, v154, s88, -v196
	v_exp_f32_e32 v154, v154
	v_fma_f32 v155, v155, s88, -v196
	v_add_f32_e32 v197, v167, v166
	v_exp_f32_e32 v155, v155
	v_fma_f32 v156, v156, s88, -v196
	v_add_f32_e32 v197, v168, v197
	v_exp_f32_e32 v156, v156
	v_fma_f32 v157, v157, s88, -v196
	v_add_f32_e32 v197, v169, v197
	v_exp_f32_e32 v157, v157
	v_fma_f32 v150, v150, s88, -v196
	v_add_f32_e32 v197, v154, v197
	v_exp_f32_e32 v150, v150
	v_fma_f32 v151, v151, s88, -v196
	v_add_f32_e32 v197, v155, v197
	v_exp_f32_e32 v151, v151
	v_fma_f32 v152, v152, s88, -v196
	v_add_f32_e32 v197, v156, v197
	v_exp_f32_e32 v152, v152
	v_fma_f32 v153, v153, s88, -v196
	v_add_f32_e32 v197, v157, v197
	v_exp_f32_e32 v153, v153
	v_fma_f32 v142, v142, s88, -v196
	v_add_f32_e32 v197, v150, v197
	v_exp_f32_e32 v198, v142
	v_fma_f32 v142, v143, s88, -v196
	v_add_f32_e32 v197, v151, v197
	v_exp_f32_e32 v199, v142
	v_fma_f32 v142, v144, s88, -v196
	v_add_f32_e32 v197, v152, v197
	v_exp_f32_e32 v205, v142
	v_fma_f32 v142, v145, s88, -v196
	v_add_f32_e32 v197, v153, v197
	v_exp_f32_e32 v196, v142
	v_add_f32_e32 v142, v198, v197
	v_add_f32_e32 v142, v199, v142
	v_add_f32_e32 v142, v205, v142
	v_add_f32_e32 v142, v196, v142
	v_add_f32_e32 v225, v225, v142
	v_cvt_pk_bf16_f32 v142, v166, v167
	v_cvt_pk_bf16_f32 v143, v168, v169
	v_cvt_pk_bf16_f32 v144, v154, v155
	v_cvt_pk_bf16_f32 v145, v156, v157
	v_cvt_pk_bf16_f32 v170, v252, v231
	v_cvt_pk_bf16_f32 v171, v229, v230
	v_cvt_pk_bf16_f32 v229, v246, v247
	v_cvt_pk_bf16_f32 v230, v248, v249
	v_cvt_pk_bf16_f32 v231, v250, v251
	v_cvt_pk_bf16_f32 v246, v150, v151
	v_cvt_pk_bf16_f32 v247, v152, v153
	v_cvt_pk_bf16_f32 v248, v198, v199
	v_cvt_pk_bf16_f32 v249, v205, v196
	s_setprio 1
	v_add3_u32 v196, s71, v240, v239
	ds_read_b64_tr_b16 v[152:153], v196 offset:15872
	ds_read_b64_tr_b16 v[150:151], v196 offset:13312
	ds_read_b64_tr_b16 v[154:155], v196 offset:13344
	ds_read_b64_tr_b16 v[156:157], v196 offset:15904
	ds_read_b64_tr_b16 v[166:167], v196 offset:13376
	ds_read_b64_tr_b16 v[168:169], v196 offset:15936
	s_mov_b64 s[20:21], 0
	s_waitcnt lgkmcnt(4)
	v_mfma_f32_16x16x32_bf16 v[158:161], v[150:153], v[228:231], v[90:93]
	v_mfma_f32_16x16x32_bf16 v[150:153], v[150:153], v[142:145], v[82:85]
	v_mov_b64_e32 v[218:219], v[224:225]
	s_waitcnt lgkmcnt(0)
	v_mfma_f32_16x16x32_bf16 v[182:185], v[166:169], v[228:231], v[74:77]
	s_nop 2
	ds_read_b64_tr_b16 v[146:147], v196 offset:13408
	ds_read_b64_tr_b16 v[148:149], v196 offset:15968
	v_mfma_f32_16x16x32_bf16 v[162:165], v[154:157], v[228:231], v[86:89]
	v_mov_b64_e32 v[220:221], v[222:223]
	v_mfma_f32_16x16x32_bf16 v[154:157], v[154:157], v[142:145], v[78:81]
	v_mfma_f32_16x16x32_bf16 v[166:169], v[166:169], v[142:145], v[70:73]
	s_waitcnt lgkmcnt(0)
	v_mfma_f32_16x16x32_bf16 v[174:177], v[146:149], v[142:145], v[62:65]
	ds_read_b64_tr_b16 v[142:143], v196 offset:18432
	ds_read_b64_tr_b16 v[144:145], v196 offset:20992
	v_mfma_f32_16x16x32_bf16 v[178:181], v[146:149], v[228:231], v[66:69]
	s_waitcnt lgkmcnt(0)
	v_mfma_f32_16x16x32_bf16 v[90:93], v[142:145], v[170:173], v[158:161]
	v_mfma_f32_16x16x32_bf16 v[82:85], v[142:145], v[246:249], v[150:153]
	s_nop 2
	ds_read_b64_tr_b16 v[150:151], v196 offset:18464
	ds_read_b64_tr_b16 v[152:153], v196 offset:21024
	ds_read_b64_tr_b16 v[158:159], v196 offset:18496
	ds_read_b64_tr_b16 v[160:161], v196 offset:21056
	s_waitcnt lgkmcnt(2)
	v_mfma_f32_16x16x32_bf16 v[86:89], v[150:153], v[170:173], v[162:165]
	s_nop 2
	ds_read_b64_tr_b16 v[162:163], v196 offset:18528
	ds_read_b64_tr_b16 v[164:165], v196 offset:21088
	v_mfma_f32_16x16x32_bf16 v[78:81], v[150:153], v[246:249], v[154:157]
	s_waitcnt lgkmcnt(2)
	v_mfma_f32_16x16x32_bf16 v[74:77], v[158:161], v[170:173], v[182:185]
	v_mfma_f32_16x16x32_bf16 v[70:73], v[158:161], v[246:249], v[166:169]
	s_waitcnt lgkmcnt(0)
	v_mfma_f32_16x16x32_bf16 v[66:69], v[162:165], v[170:173], v[178:181]
	v_mfma_f32_16x16x32_bf16 v[62:65], v[162:165], v[246:249], v[174:177]
	s_setprio 0
	s_branch .LBB0_797

; #define LAS __attribute__((address_space(3)))
; __device__ __forceinline__ float ex2(float x) { return __builtin_amdgcn_exp2f(x); }
; #define LBAR() asm volatile("s_waitcnt lgkmcnt(0)\n\ts_barrier" ::: "memory")
; template <int NT, int NKK, int NDT, int MODE, bool MASK> ...
;   const int r = lane & 15, lg = lane >> 4, vq = (lane & 15) >> 2, vp = lane & 3;
;   f32x4 s[NT][4];
;   __builtin_amdgcn_s_setprio(1);
; #pragma unroll
;   for (int t = 0; t < 4; ++t)
; #pragma unroll
;     for (int kk = 0; kk < NKK; ++kk) {
;       const bf16x8 kf = *(LAS const bf16x8*)(Kl + (16 * t + r) * KSTR + (32 * kk + 8 * lg) * 2);
; #pragma unroll
;       for (int j = 0; j < NT; ++j) s[j][t] = mfma16(kf, qf[j][kk], kk == 0 ? (f32x4){0.f, 0.f, 0.f, 0.f} : s[j][t]);
;     }
;   __builtin_amdgcn_s_setprio(0);
;   bf16x8 pf[NT][2];
; #pragma unroll
;   for (int j = 0; j < NT; ++j) {
;     float mx = -INFINITY;
; #pragma unroll
;     for (int t = 0; t < 4; ++t)
; #pragma unroll
;       for (int i = 0; i < 4; ++i) {
;         if (MASK) { const int kp = kpos0 + 16 * t + 4 * lg + i; if (!mask_ok<MODE>(tq[j], kp, W)) s[j][t][i] = -INFINITY; }
;         mx = fmaxf(mx, s[j][t][i]);
;       }
;     mx = max_x16_x32(mx);
;     if (__any(mx > m[j] + 8.0f / c)) {
;       const float mnew = fmaxf(m[j], mx);
;       const float ms2 = (mnew == -INFINITY) ? 0.f : mnew;
;       const float alpha = ex2((m[j] - ms2) * c);
;       m[j] = mnew; l[j] *= alpha;
; #pragma unroll
;       for (int dt = 0; dt < NDT; ++dt) o[j][dt] *= alpha;
;     }
; template <int NT, int DQK, int DV, int MODE, int PD, class Src> ...
;     ...
;         LBAR();
;         const int lo = kbase + 64 * kc, hi = lo + 63;
;         bool rel = true, full = true;
;         if (MODE == MODE_CAUSAL) { rel = lo <= tq_max; full = hi <= tq_min; }
;         if (MODE == MODE_WINDOW) { rel = (lo <= tq_max) && (hi > tq_min - W); full = (hi <= tq_min) && (lo > tq_max - W); }
;         if (MODE == MODE_CMP) { rel = 16 * lo + 31 <= tq_max; full = 16 * hi + 31 <= tq_min; }
;         if (rel) {
;           if (NT <= 2) {
;             if (full) attn_chunk_wide<NT, DQK / 32, DV / 16, MODE, false>(o, m, l, qf, buf, KSTR, buf + KB, VSTR, lo, tq, c, W, lane);
;             else attn_chunk_wide<NT, DQK / 32, DV / 16, MODE, true>(o, m, l, qf, buf, KSTR, buf + KB, VSTR, lo, tq, c, W, lane);
.LBB0_810:
	s_waitcnt lgkmcnt(0)
	s_barrier
	s_add_i32 s8, s69, 0xffffff81
	s_cmp_gt_i32 s8, s68
	s_cbranch_scc1 .LBB0_837
	s_sub_i32 s8, s69, 64
	s_cmp_gt_i32 s8, s59
	s_setprio 1
	v_add_u32_e32 v1, s73, v236
	s_waitcnt lgkmcnt(0)
	v_add_u32_e32 v94, v1, v237
	ds_read_b128 v[134:137], v94
	ds_read_b128 v[130:133], v94 offset:64
	ds_read_b128 v[126:129], v94 offset:128
	ds_read_b128 v[122:125], v94 offset:3328
	ds_read_b128 v[118:121], v94 offset:3392
	ds_read_b128 v[114:117], v94 offset:3456
	ds_read_b128 v[106:109], v94 offset:6656
	ds_read_b128 v[98:101], v94 offset:6720
	v_add_u32_e32 v201, v1, v238
	ds_read_b128 v[110:113], v94 offset:6784
	ds_read_b128 v[102:105], v201
	ds_read_b128 v[94:97], v201 offset:64
	s_mov_b64 s[20:21], -1
	v_add_f32_e32 v1, 0x4259535f, v220
	s_cbranch_scc1 .LBB0_828
	s_waitcnt lgkmcnt(10)
	v_mfma_f32_16x16x32_bf16 v[138:141], v[134:137], v[18:21], 0
	ds_read_b128 v[146:149], v201 offset:128
	v_mov_b32_e32 v234, 0x260
	v_mfma_f32_16x16x32_bf16 v[142:145], v[134:137], v[10:13], 0
	s_waitcnt lgkmcnt(10)
	v_mfma_f32_16x16x32_bf16 v[138:141], v[130:133], v[2:5], v[138:141]
	v_mov_b64_e32 v[222:223], v[220:221]
	v_mfma_f32_16x16x32_bf16 v[142:145], v[130:133], v[14:17], v[142:145]
	v_mov_b64_e32 v[224:225], v[218:219]
	s_waitcnt lgkmcnt(9)
	v_mfma_f32_16x16x32_bf16 v[182:185], v[126:129], v[6:9], v[138:141]
	v_mfma_f32_16x16x32_bf16 v[166:169], v[126:129], v[22:25], v[142:145]
	v_mov_b32_e32 v187, v220
	s_waitcnt lgkmcnt(8)
	v_mfma_f32_16x16x32_bf16 v[138:141], v[122:125], v[18:21], 0
	v_mfma_f32_16x16x32_bf16 v[142:145], v[122:125], v[10:13], 0
	s_waitcnt lgkmcnt(7)
	v_mfma_f32_16x16x32_bf16 v[138:141], v[118:121], v[2:5], v[138:141]
	v_mfma_f32_16x16x32_bf16 v[142:145], v[118:121], v[14:17], v[142:145]
	s_waitcnt lgkmcnt(6)
	v_mfma_f32_16x16x32_bf16 v[178:181], v[114:117], v[6:9], v[138:141]
	v_mfma_f32_16x16x32_bf16 v[154:157], v[114:117], v[22:25], v[142:145]
	s_waitcnt lgkmcnt(5)
	v_mfma_f32_16x16x32_bf16 v[138:141], v[106:109], v[18:21], 0
	v_mfma_f32_16x16x32_bf16 v[142:145], v[106:109], v[10:13], 0
	v_max3_f32 v188, v182, s81, v183
	s_waitcnt lgkmcnt(4)
	v_mfma_f32_16x16x32_bf16 v[138:141], v[98:101], v[2:5], v[138:141]
	v_max3_f32 v188, v188, v184, v185
	v_mfma_f32_16x16x32_bf16 v[142:145], v[98:101], v[14:17], v[142:145]
	v_max3_f32 v189, v166, s81, v167
	s_waitcnt lgkmcnt(3)
	v_mfma_f32_16x16x32_bf16 v[174:177], v[110:113], v[6:9], v[138:141]
	v_max3_f32 v189, v189, v168, v169
	v_mfma_f32_16x16x32_bf16 v[150:153], v[110:113], v[22:25], v[142:145]
	s_waitcnt lgkmcnt(2)
	v_mfma_f32_16x16x32_bf16 v[138:141], v[102:105], v[18:21], 0
	v_mfma_f32_16x16x32_bf16 v[142:145], v[102:105], v[10:13], 0
	v_max3_f32 v188, v188, v178, v179
	s_waitcnt lgkmcnt(1)
	v_mfma_f32_16x16x32_bf16 v[138:141], v[94:97], v[2:5], v[138:141]
	v_max3_f32 v188, v188, v180, v181
	v_mfma_f32_16x16x32_bf16 v[142:145], v[94:97], v[14:17], v[142:145]
	v_max3_f32 v189, v189, v154, v155
	s_waitcnt lgkmcnt(0)
	v_mfma_f32_16x16x32_bf16 v[170:173], v[146:149], v[6:9], v[138:141]
	v_max3_f32 v189, v189, v156, v157
	v_mfma_f32_16x16x32_bf16 v[142:145], v[146:149], v[22:25], v[142:145]
	s_setprio 0
	s_nop 3
	v_max3_f32 v138, v188, v174, v175
	v_max3_f32 v138, v138, v176, v177
	v_max3_f32 v138, v138, v170, v171
	v_max3_f32 v138, v138, v172, v173
	v_mov_b32_e32 v139, v138
	s_nop 1
	v_permlane16_swap_b32_e32 v138, v139
	v_max_f32_e32 v138, v138, v139
	v_mov_b32_e32 v139, v138
	s_nop 1
	v_permlane32_swap_b32_e32 v138, v139
	v_max_f32_e32 v186, v138, v139
	v_cmp_gt_f32_e32 vcc, v186, v1
	s_cbranch_vccz .LBB0_814
	v_max_f32_e32 v138, v186, v186
	v_max_f32_e32 v139, v220, v220
	v_max_f32_e32 v222, v139, v138
	v_cmp_neq_f32_e32 vcc, s81, v222
	v_mov_b32_e32 v223, v221
	v_mov_b32_e32 v225, v219
	v_cndmask_b32_e32 v138, 0, v222, vcc
	v_sub_f32_e32 v138, v220, v138
	v_mul_f32_e32 v138, 0x3e16c740, v138
	v_exp_f32_e32 v138, v138
	v_mov_b32_e32 v187, v222
	v_mul_f32_e32 v224, v218, v138
	v_pk_mul_f32 v[92:93], v[92:93], v[138:139] op_sel_hi:[1,0]
	v_pk_mul_f32 v[90:91], v[90:91], v[138:139] op_sel_hi:[1,0]
	v_pk_mul_f32 v[88:89], v[88:89], v[138:139] op_sel_hi:[1,0]
	v_pk_mul_f32 v[86:87], v[86:87], v[138:139] op_sel_hi:[1,0]
	v_pk_mul_f32 v[76:77], v[76:77], v[138:139] op_sel_hi:[1,0]
	v_pk_mul_f32 v[74:75], v[74:75], v[138:139] op_sel_hi:[1,0]
	v_pk_mul_f32 v[68:69], v[68:69], v[138:139] op_sel_hi:[1,0]
	v_pk_mul_f32 v[66:67], v[66:67], v[138:139] op_sel_hi:[1,0]

; __device__ __forceinline__ float ex2(float x) { return __builtin_amdgcn_exp2f(x); }
; __device__ __forceinline__ f32x4 mfma16(bf16x8 a, bf16x8 b, f32x4 c) { return __builtin_amdgcn_mfma_f32_16x16x32_bf16(a, b, c, 0, 0, 0); }
; __device__ __forceinline__ s16x4 ds_tr(LAS const unsigned char* p) { return __builtin_bit_cast(s16x4, __builtin_amdgcn_ds_read_tr16_b64_v4i16((LAS v4i16_t*)p)); }
; template <int NT, int NKK, int NDT, int MODE, bool MASK> ...
;     ...
;     const float mc = ((m[j] == -INFINITY) ? 0.f : m[j]) * c;
;     float p[4][4], ps = 0.f;
; #pragma unroll
;     for (int t = 0; t < 4; ++t)
; #pragma unroll
;       for (int i = 0; i < 4; ++i) { p[t][i] = ex2(s[j][t][i] * c - mc); ps += p[t][i]; }
;     l[j] += ps;
;     pf[j][0] = pack8(p[0], p[1]); pf[j][1] = pack8(p[2], p[3]);
;   }
;   __builtin_amdgcn_s_setprio(1);
; #pragma unroll
;   for (int st = 0; st < 2; ++st)
; #pragma unroll
;     for (int dt = 0; dt < NDT; ++dt) {
;       const s16x4 v0 = ds_tr(Vl + (32 * st + 4 * lg + vq) * VSTR + (16 * dt + 4 * vp) * 2);
;       const s16x4 v1 = ds_tr(Vl + (32 * st + 16 + 4 * lg + vq) * VSTR + (16 * dt + 4 * vp) * 2);
;       const bf16x8 vf = (bf16x8){v0[0], v0[1], v0[2], v0[3], v1[0], v1[1], v1[2], v1[3]};
; #pragma unroll
;       for (int j = 0; j < NT; ++j) o[j][dt] = mfma16(vf, pf[j][st], o[j][dt]);
;     }
;   __builtin_amdgcn_s_setprio(0);
.LBB0_827:
	v_cvt_pk_bf16_f32 v173, v196, v173
	v_mul_f32_e32 v196, 0x3e16c740, v197
	v_cmp_neq_f32_e32 vcc, s81, v197
	v_cvt_pk_bf16_f32 v172, v232, v228
	v_cvt_pk_bf16_f32 v228, v205, v207
	v_cndmask_b32_e32 v196, 0, v196, vcc
	v_fma_f32 v166, v166, s88, -v196
	v_exp_f32_e32 v166, v166
	v_fma_f32 v167, v167, s88, -v196
	v_exp_f32_e32 v167, v167
	v_fma_f32 v168, v168, s88, -v196
	v_exp_f32_e32 v168, v168
	v_fma_f32 v169, v169, s88, -v196
	v_exp_f32_e32 v169, v169
	v_fma_f32 v154, v154, s88, -v196
	v_exp_f32_e32 v154, v154
	v_fma_f32 v155, v155, s88, -v196
	v_add_f32_e32 v197, v167, v166
	v_exp_f32_e32 v155, v155
	v_fma_f32 v156, v156, s88, -v196
	v_add_f32_e32 v197, v168, v197
	v_exp_f32_e32 v156, v156
	v_fma_f32 v157, v157, s88, -v196
	v_add_f32_e32 v197, v169, v197
	v_exp_f32_e32 v157, v157
	v_fma_f32 v150, v150, s88, -v196
	v_add_f32_e32 v197, v154, v197
	v_exp_f32_e32 v150, v150
	v_fma_f32 v151, v151, s88, -v196
	v_add_f32_e32 v197, v155, v197
	v_exp_f32_e32 v151, v151
	v_fma_f32 v152, v152, s88, -v196
	v_add_f32_e32 v197, v156, v197
	v_exp_f32_e32 v152, v152
	v_fma_f32 v153, v153, s88, -v196
	v_add_f32_e32 v197, v157, v197
	v_exp_f32_e32 v153, v153
	v_fma_f32 v142, v142, s88, -v196
	v_add_f32_e32 v197, v150, v197
	v_exp_f32_e32 v198, v142
	v_fma_f32 v142, v143, s88, -v196
	v_add_f32_e32 v197, v151, v197
	v_exp_f32_e32 v199, v142
	v_fma_f32 v142, v144, s88, -v196
	v_add_f32_e32 v197, v152, v197
	v_exp_f32_e32 v205, v142
	v_fma_f32 v142, v145, s88, -v196
	v_add_f32_e32 v197, v153, v197
	v_exp_f32_e32 v196, v142
	v_add_f32_e32 v142, v198, v197
	v_add_f32_e32 v142, v199, v142
	v_add_f32_e32 v142, v205, v142
	v_add_f32_e32 v142, v196, v142
	v_add_f32_e32 v225, v225, v142
	v_cvt_pk_bf16_f32 v142, v166, v167
	v_cvt_pk_bf16_f32 v143, v168, v169
	v_cvt_pk_bf16_f32 v144, v154, v155
	v_cvt_pk_bf16_f32 v145, v156, v157
	v_cvt_pk_bf16_f32 v170, v252, v231
	v_cvt_pk_bf16_f32 v171, v229, v230
	v_cvt_pk_bf16_f32 v229, v246, v247
	v_cvt_pk_bf16_f32 v230, v248, v249
	v_cvt_pk_bf16_f32 v231, v250, v251
	v_cvt_pk_bf16_f32 v246, v150, v151
	v_cvt_pk_bf16_f32 v247, v152, v153
	v_cvt_pk_bf16_f32 v248, v198, v199
	v_cvt_pk_bf16_f32 v249, v205, v196
	s_setprio 1
	v_add3_u32 v196, s73, v240, v239
	ds_read_b64_tr_b16 v[152:153], v196 offset:15872
	ds_read_b64_tr_b16 v[150:151], v196 offset:13312
	ds_read_b64_tr_b16 v[154:155], v196 offset:13344
	ds_read_b64_tr_b16 v[156:157], v196 offset:15904
	ds_read_b64_tr_b16 v[166:167], v196 offset:13376
	ds_read_b64_tr_b16 v[168:169], v196 offset:15936
	s_mov_b64 s[20:21], 0
	s_waitcnt lgkmcnt(4)
	v_mfma_f32_16x16x32_bf16 v[158:161], v[150:153], v[228:231], v[90:93]
	v_mfma_f32_16x16x32_bf16 v[150:153], v[150:153], v[142:145], v[82:85]
	v_mov_b64_e32 v[218:219], v[224:225]
	s_waitcnt lgkmcnt(0)
	v_mfma_f32_16x16x32_bf16 v[182:185], v[166:169], v[228:231], v[74:77]
	s_nop 2
	ds_read_b64_tr_b16 v[146:147], v196 offset:13408
	ds_read_b64_tr_b16 v[148:149], v196 offset:15968
	v_mfma_f32_16x16x32_bf16 v[162:165], v[154:157], v[228:231], v[86:89]
	v_mov_b64_e32 v[220:221], v[222:223]
	v_mfma_f32_16x16x32_bf16 v[154:157], v[154:157], v[142:145], v[78:81]
	v_mfma_f32_16x16x32_bf16 v[166:169], v[166:169], v[142:145], v[70:73]
	s_waitcnt lgkmcnt(0)
	v_mfma_f32_16x16x32_bf16 v[174:177], v[146:149], v[142:145], v[62:65]
	ds_read_b64_tr_b16 v[142:143], v196 offset:18432
	ds_read_b64_tr_b16 v[144:145], v196 offset:20992
	v_mfma_f32_16x16x32_bf16 v[178:181], v[146:149], v[228:231], v[66:69]
	s_waitcnt lgkmcnt(0)
	v_mfma_f32_16x16x32_bf16 v[90:93], v[142:145], v[170:173], v[158:161]
	v_mfma_f32_16x16x32_bf16 v[82:85], v[142:145], v[246:249], v[150:153]
	s_nop 2
	ds_read_b64_tr_b16 v[150:151], v196 offset:18464
	ds_read_b64_tr_b16 v[152:153], v196 offset:21024
	ds_read_b64_tr_b16 v[158:159], v196 offset:18496
	ds_read_b64_tr_b16 v[160:161], v196 offset:21056
	s_waitcnt lgkmcnt(2)
	v_mfma_f32_16x16x32_bf16 v[86:89], v[150:153], v[170:173], v[162:165]
	s_nop 2
	ds_read_b64_tr_b16 v[162:163], v196 offset:18528
	ds_read_b64_tr_b16 v[164:165], v196 offset:21088
	v_mfma_f32_16x16x32_bf16 v[78:81], v[150:153], v[246:249], v[154:157]
	s_waitcnt lgkmcnt(2)
	v_mfma_f32_16x16x32_bf16 v[74:77], v[158:161], v[170:173], v[182:185]
	v_mfma_f32_16x16x32_bf16 v[70:73], v[158:161], v[246:249], v[166:169]
	s_waitcnt lgkmcnt(0)
	v_mfma_f32_16x16x32_bf16 v[66:69], v[162:165], v[170:173], v[178:181]
	v_mfma_f32_16x16x32_bf16 v[62:65], v[162:165], v[246:249], v[174:177]
	s_setprio 0
	s_branch .LBB0_837

; #define LAS __attribute__((address_space(3)))
; __device__ __forceinline__ float ex2(float x) { return __builtin_amdgcn_exp2f(x); }
; #define LBAR() asm volatile("s_waitcnt lgkmcnt(0)\n\ts_barrier" ::: "memory")
; template <int NT, int NKK, int NDT, int MODE, bool MASK> ...
;   const int r = lane & 15, lg = lane >> 4, vq = (lane & 15) >> 2, vp = lane & 3;
;   f32x4 s[NT][4];
;   __builtin_amdgcn_s_setprio(1);
; #pragma unroll
;   for (int t = 0; t < 4; ++t)
; #pragma unroll
;     for (int kk = 0; kk < NKK; ++kk) {
;       const bf16x8 kf = *(LAS const bf16x8*)(Kl + (16 * t + r) * KSTR + (32 * kk + 8 * lg) * 2);
; #pragma unroll
;       for (int j = 0; j < NT; ++j) s[j][t] = mfma16(kf, qf[j][kk], kk == 0 ? (f32x4){0.f, 0.f, 0.f, 0.f} : s[j][t]);
;     }
;   __builtin_amdgcn_s_setprio(0);
;   bf16x8 pf[NT][2];
; #pragma unroll
;   for (int j = 0; j < NT; ++j) {
;     float mx = -INFINITY;
; #pragma unroll
;     for (int t = 0; t < 4; ++t)
; #pragma unroll
;       for (int i = 0; i < 4; ++i) {
;         if (MASK) { const int kp = kpos0 + 16 * t + 4 * lg + i; if (!mask_ok<MODE>(tq[j], kp, W)) s[j][t][i] = -INFINITY; }
;         mx = fmaxf(mx, s[j][t][i]);
;       }
;     mx = max_x16_x32(mx);
;     if (__any(mx > m[j] + 8.0f / c)) {
;       const float mnew = fmaxf(m[j], mx);
;       const float ms2 = (mnew == -INFINITY) ? 0.f : mnew;
;       const float alpha = ex2((m[j] - ms2) * c);
;       m[j] = mnew; l[j] *= alpha;
; #pragma unroll
;       for (int dt = 0; dt < NDT; ++dt) o[j][dt] *= alpha;
;     }
; template <int NT, int DQK, int DV, int MODE, int PD, class Src> ...
;     ...
;         LBAR();
;         const int lo = kbase + 64 * kc, hi = lo + 63;
;         bool rel = true, full = true;
;         if (MODE == MODE_CAUSAL) { rel = lo <= tq_max; full = hi <= tq_min; }
;         if (MODE == MODE_WINDOW) { rel = (lo <= tq_max) && (hi > tq_min - W); full = (hi <= tq_min) && (lo > tq_max - W); }
;         if (MODE == MODE_CMP) { rel = 16 * lo + 31 <= tq_max; full = 16 * hi + 31 <= tq_min; }
;         if (rel) {
;           if (NT <= 2) {
;             if (full) attn_chunk_wide<NT, DQK / 32, DV / 16, MODE, false>(o, m, l, qf, buf, KSTR, buf + KB, VSTR, lo, tq, c, W, lane);
;             else attn_chunk_wide<NT, DQK / 32, DV / 16, MODE, true>(o, m, l, qf, buf, KSTR, buf + KB, VSTR, lo, tq, c, W, lane);
.LBB0_850:
	s_waitcnt lgkmcnt(0)
	s_barrier
	s_sub_i32 s8, s69, 63
	s_cmp_gt_i32 s8, s68
	s_cbranch_scc1 .LBB0_877
	s_cmp_gt_i32 s69, s59
	s_setprio 1
	v_add_u32_e32 v1, s71, v236
	s_waitcnt lgkmcnt(0)
	v_add_u32_e32 v94, v1, v237
	ds_read_b128 v[134:137], v94
	ds_read_b128 v[130:133], v94 offset:64
	ds_read_b128 v[126:129], v94 offset:128
	ds_read_b128 v[122:125], v94 offset:3328
	ds_read_b128 v[118:121], v94 offset:3392
	ds_read_b128 v[114:117], v94 offset:3456
	ds_read_b128 v[106:109], v94 offset:6656
	ds_read_b128 v[98:101], v94 offset:6720
	v_add_u32_e32 v201, v1, v238
	ds_read_b128 v[110:113], v94 offset:6784
	ds_read_b128 v[102:105], v201
	ds_read_b128 v[94:97], v201 offset:64
	s_mov_b64 s[20:21], -1
	v_add_f32_e32 v1, 0x4259535f, v220
	s_cbranch_scc1 .LBB0_868
	s_waitcnt lgkmcnt(10)
	v_mfma_f32_16x16x32_bf16 v[138:141], v[134:137], v[18:21], 0
	ds_read_b128 v[146:149], v201 offset:128
	v_mov_b32_e32 v234, 0x260
	v_mfma_f32_16x16x32_bf16 v[142:145], v[134:137], v[10:13], 0
	s_waitcnt lgkmcnt(10)
	v_mfma_f32_16x16x32_bf16 v[138:141], v[130:133], v[2:5], v[138:141]
	v_mov_b64_e32 v[222:223], v[220:221]
	v_mfma_f32_16x16x32_bf16 v[142:145], v[130:133], v[14:17], v[142:145]
	v_mov_b64_e32 v[224:225], v[218:219]
	s_waitcnt lgkmcnt(9)
	v_mfma_f32_16x16x32_bf16 v[182:185], v[126:129], v[6:9], v[138:141]
	v_mfma_f32_16x16x32_bf16 v[166:169], v[126:129], v[22:25], v[142:145]
	v_mov_b32_e32 v187, v220
	s_waitcnt lgkmcnt(8)
	v_mfma_f32_16x16x32_bf16 v[138:141], v[122:125], v[18:21], 0
	v_mfma_f32_16x16x32_bf16 v[142:145], v[122:125], v[10:13], 0
	s_waitcnt lgkmcnt(7)
	v_mfma_f32_16x16x32_bf16 v[138:141], v[118:121], v[2:5], v[138:141]
	v_mfma_f32_16x16x32_bf16 v[142:145], v[118:121], v[14:17], v[142:145]
	s_waitcnt lgkmcnt(6)
	v_mfma_f32_16x16x32_bf16 v[178:181], v[114:117], v[6:9], v[138:141]
	v_mfma_f32_16x16x32_bf16 v[154:157], v[114:117], v[22:25], v[142:145]
	s_waitcnt lgkmcnt(5)
	v_mfma_f32_16x16x32_bf16 v[138:141], v[106:109], v[18:21], 0
	v_mfma_f32_16x16x32_bf16 v[142:145], v[106:109], v[10:13], 0
	v_max3_f32 v188, v182, s81, v183
	s_waitcnt lgkmcnt(4)
	v_mfma_f32_16x16x32_bf16 v[138:141], v[98:101], v[2:5], v[138:141]
	v_max3_f32 v188, v188, v184, v185
	v_mfma_f32_16x16x32_bf16 v[142:145], v[98:101], v[14:17], v[142:145]
	v_max3_f32 v189, v166, s81, v167
	s_waitcnt lgkmcnt(3)
	v_mfma_f32_16x16x32_bf16 v[174:177], v[110:113], v[6:9], v[138:141]
	v_max3_f32 v189, v189, v168, v169
	v_mfma_f32_16x16x32_bf16 v[150:153], v[110:113], v[22:25], v[142:145]
	s_waitcnt lgkmcnt(2)
	v_mfma_f32_16x16x32_bf16 v[138:141], v[102:105], v[18:21], 0
	v_mfma_f32_16x16x32_bf16 v[142:145], v[102:105], v[10:13], 0
	v_max3_f32 v188, v188, v178, v179
	s_waitcnt lgkmcnt(1)
	v_mfma_f32_16x16x32_bf16 v[138:141], v[94:97], v[2:5], v[138:141]
	v_max3_f32 v188, v188, v180, v181
	v_mfma_f32_16x16x32_bf16 v[142:145], v[94:97], v[14:17], v[142:145]
	v_max3_f32 v189, v189, v154, v155
	s_waitcnt lgkmcnt(0)
	v_mfma_f32_16x16x32_bf16 v[170:173], v[146:149], v[6:9], v[138:141]
	v_max3_f32 v189, v189, v156, v157
	v_mfma_f32_16x16x32_bf16 v[142:145], v[146:149], v[22:25], v[142:145]
	s_setprio 0
	s_nop 3
	v_max3_f32 v138, v188, v174, v175
	v_max3_f32 v138, v138, v176, v177
	v_max3_f32 v138, v138, v170, v171
	v_max3_f32 v138, v138, v172, v173
	v_mov_b32_e32 v139, v138
	s_nop 1
	v_permlane16_swap_b32_e32 v138, v139
	v_max_f32_e32 v138, v138, v139
	v_mov_b32_e32 v139, v138
	s_nop 1
	v_permlane32_swap_b32_e32 v138, v139
	v_max_f32_e32 v186, v138, v139
	v_cmp_gt_f32_e32 vcc, v186, v1
	s_cbranch_vccz .LBB0_854
	v_max_f32_e32 v138, v186, v186
	v_max_f32_e32 v139, v220, v220
	v_max_f32_e32 v222, v139, v138
	v_cmp_neq_f32_e32 vcc, s81, v222
	v_mov_b32_e32 v223, v221
	v_mov_b32_e32 v225, v219
	v_cndmask_b32_e32 v138, 0, v222, vcc
	v_sub_f32_e32 v138, v220, v138
	v_mul_f32_e32 v138, 0x3e16c740, v138
	v_exp_f32_e32 v138, v138
	v_mov_b32_e32 v187, v222
	v_mul_f32_e32 v224, v218, v138
	v_pk_mul_f32 v[92:93], v[92:93], v[138:139] op_sel_hi:[1,0]
	v_pk_mul_f32 v[90:91], v[90:91], v[138:139] op_sel_hi:[1,0]
	v_pk_mul_f32 v[88:89], v[88:89], v[138:139] op_sel_hi:[1,0]
	v_pk_mul_f32 v[86:87], v[86:87], v[138:139] op_sel_hi:[1,0]
	v_pk_mul_f32 v[76:77], v[76:77], v[138:139] op_sel_hi:[1,0]
	v_pk_mul_f32 v[74:75], v[74:75], v[138:139] op_sel_hi:[1,0]
	v_pk_mul_f32 v[68:69], v[68:69], v[138:139] op_sel_hi:[1,0]
	v_pk_mul_f32 v[66:67], v[66:67], v[138:139] op_sel_hi:[1,0]

; #define LAS __attribute__((address_space(3)))
; __device__ __forceinline__ float ex2(float x) { return __builtin_amdgcn_exp2f(x); }
; #define LBAR() asm volatile("s_waitcnt lgkmcnt(0)\n\ts_barrier" ::: "memory")
; template <int NT, int NKK, int NDT, int MODE, bool MASK> ...
;   const int r = lane & 15, lg = lane >> 4, vq = (lane & 15) >> 2, vp = lane & 3;
;   f32x4 s[NT][4];
;   __builtin_amdgcn_s_setprio(1);
; #pragma unroll
;   for (int t = 0; t < 4; ++t)
; #pragma unroll
;     for (int kk = 0; kk < NKK; ++kk) {
;       const bf16x8 kf = *(LAS const bf16x8*)(Kl + (16 * t + r) * KSTR + (32 * kk + 8 * lg) * 2);
; #pragma unroll
;       for (int j = 0; j < NT; ++j) s[j][t] = mfma16(kf, qf[j][kk], kk == 0 ? (f32x4){0.f, 0.f, 0.f, 0.f} : s[j][t]);
;     }
;   __builtin_amdgcn_s_setprio(0);
;   bf16x8 pf[NT][2];
; #pragma unroll
;   for (int j = 0; j < NT; ++j) {
;     float mx = -INFINITY;
; #pragma unroll
;     for (int t = 0; t < 4; ++t)
; #pragma unroll
;       for (int i = 0; i < 4; ++i) {
;         if (MASK) { const int kp = kpos0 + 16 * t + 4 * lg + i; if (!mask_ok<MODE>(tq[j], kp, W)) s[j][t][i] = -INFINITY; }
;         mx = fmaxf(mx, s[j][t][i]);
;       }
;     mx = max_x16_x32(mx);
;     if (__any(mx > m[j] + 8.0f / c)) {
;       const float mnew = fmaxf(m[j], mx);
;       const float ms2 = (mnew == -INFINITY) ? 0.f : mnew;
;       const float alpha = ex2((m[j] - ms2) * c);
;       m[j] = mnew; l[j] *= alpha;
; #pragma unroll
;       for (int dt = 0; dt < NDT; ++dt) o[j][dt] *= alpha;
;     }
; template <int NT, int DQK, int DV, int MODE, int PD, class Src> ...
;     ...
;         LBAR();
;         const int lo = kbase + 64 * kc, hi = lo + 63;
;         bool rel = true, full = true;
;         if (MODE == MODE_CAUSAL) { rel = lo <= tq_max; full = hi <= tq_min; }
;         if (MODE == MODE_WINDOW) { rel = (lo <= tq_max) && (hi > tq_min - W); full = (hi <= tq_min) && (lo > tq_max - W); }
;         if (MODE == MODE_CMP) { rel = 16 * lo + 31 <= tq_max; full = 16 * hi + 31 <= tq_min; }
;         if (rel) {
;           if (NT <= 2) {
;             if (full) attn_chunk_wide<NT, DQK / 32, DV / 16, MODE, false>(o, m, l, qf, buf, KSTR, buf + KB, VSTR, lo, tq, c, W, lane);
;             else attn_chunk_wide<NT, DQK / 32, DV / 16, MODE, true>(o, m, l, qf, buf, KSTR, buf + KB, VSTR, lo, tq, c, W, lane);
.LBB0_941:
	s_waitcnt lgkmcnt(0)
	s_barrier
	s_add_i32 s8, s43, 0xffffff41
	s_cmp_gt_i32 s8, s40
	s_cbranch_scc1 .LBB0_970
	s_add_i32 s8, s43, 0xffffff80
	s_cmp_gt_i32 s8, s25
	s_setprio 1
	v_add_u32_e32 v1, s45, v236
	s_waitcnt lgkmcnt(0)
	v_add_u32_e32 v94, v1, v237
	ds_read_b128 v[134:137], v94
	ds_read_b128 v[130:133], v94 offset:64
	ds_read_b128 v[126:129], v94 offset:128
	ds_read_b128 v[122:125], v94 offset:3328
	ds_read_b128 v[118:121], v94 offset:3392
	ds_read_b128 v[114:117], v94 offset:3456
	ds_read_b128 v[106:109], v94 offset:6656
	ds_read_b128 v[98:101], v94 offset:6720
	v_add_u32_e32 v201, v1, v238
	ds_read_b128 v[110:113], v94 offset:6784
	ds_read_b128 v[102:105], v201
	ds_read_b128 v[94:97], v201 offset:64
	s_mov_b64 s[20:21], -1
	v_add_f32_e32 v1, 0x4259535f, v220
	s_cbranch_scc1 .LBB0_961
	s_waitcnt lgkmcnt(10)
	v_mfma_f32_16x16x32_bf16 v[138:141], v[134:137], v[18:21], 0
	ds_read_b128 v[146:149], v201 offset:128
	v_mov_b32_e32 v234, 0x260
	v_mfma_f32_16x16x32_bf16 v[142:145], v[134:137], v[10:13], 0
	s_waitcnt lgkmcnt(10)
	v_mfma_f32_16x16x32_bf16 v[138:141], v[130:133], v[2:5], v[138:141]
	v_mov_b64_e32 v[222:223], v[220:221]
	v_mfma_f32_16x16x32_bf16 v[142:145], v[130:133], v[14:17], v[142:145]
	v_mov_b64_e32 v[224:225], v[218:219]
	s_waitcnt lgkmcnt(9)
	v_mfma_f32_16x16x32_bf16 v[182:185], v[126:129], v[6:9], v[138:141]
	v_mfma_f32_16x16x32_bf16 v[166:169], v[126:129], v[22:25], v[142:145]
	v_mov_b32_e32 v187, v220
	s_waitcnt lgkmcnt(8)
	v_mfma_f32_16x16x32_bf16 v[138:141], v[122:125], v[18:21], 0
	v_mfma_f32_16x16x32_bf16 v[142:145], v[122:125], v[10:13], 0
	s_waitcnt lgkmcnt(7)
	v_mfma_f32_16x16x32_bf16 v[138:141], v[118:121], v[2:5], v[138:141]
	v_mfma_f32_16x16x32_bf16 v[142:145], v[118:121], v[14:17], v[142:145]
	s_waitcnt lgkmcnt(6)
	v_mfma_f32_16x16x32_bf16 v[178:181], v[114:117], v[6:9], v[138:141]
	v_mfma_f32_16x16x32_bf16 v[154:157], v[114:117], v[22:25], v[142:145]
	s_waitcnt lgkmcnt(5)
	v_mfma_f32_16x16x32_bf16 v[138:141], v[106:109], v[18:21], 0
	v_mfma_f32_16x16x32_bf16 v[142:145], v[106:109], v[10:13], 0
	v_max3_f32 v188, v182, s81, v183
	s_waitcnt lgkmcnt(4)
	v_mfma_f32_16x16x32_bf16 v[138:141], v[98:101], v[2:5], v[138:141]
	v_max3_f32 v188, v188, v184, v185
	v_mfma_f32_16x16x32_bf16 v[142:145], v[98:101], v[14:17], v[142:145]
	v_max3_f32 v189, v166, s81, v167
	s_waitcnt lgkmcnt(3)
	v_mfma_f32_16x16x32_bf16 v[174:177], v[110:113], v[6:9], v[138:141]
	v_max3_f32 v189, v189, v168, v169
	v_mfma_f32_16x16x32_bf16 v[150:153], v[110:113], v[22:25], v[142:145]
	s_waitcnt lgkmcnt(2)
	v_mfma_f32_16x16x32_bf16 v[138:141], v[102:105], v[18:21], 0
	v_mfma_f32_16x16x32_bf16 v[142:145], v[102:105], v[10:13], 0
	v_max3_f32 v188, v188, v178, v179
	s_waitcnt lgkmcnt(1)
	v_mfma_f32_16x16x32_bf16 v[138:141], v[94:97], v[2:5], v[138:141]
	v_max3_f32 v188, v188, v180, v181
	v_mfma_f32_16x16x32_bf16 v[142:145], v[94:97], v[14:17], v[142:145]
	v_max3_f32 v189, v189, v154, v155
	s_waitcnt lgkmcnt(0)
	v_mfma_f32_16x16x32_bf16 v[170:173], v[146:149], v[6:9], v[138:141]
	v_max3_f32 v189, v189, v156, v157
	v_mfma_f32_16x16x32_bf16 v[142:145], v[146:149], v[22:25], v[142:145]
	s_setprio 0
	s_nop 3
	v_max3_f32 v138, v188, v174, v175
	v_max3_f32 v138, v138, v176, v177
	v_max3_f32 v138, v138, v170, v171
	v_max3_f32 v138, v138, v172, v173
	v_mov_b32_e32 v139, v138
	s_nop 1
	v_permlane16_swap_b32_e32 v138, v139
	v_max_f32_e32 v138, v138, v139
	v_mov_b32_e32 v139, v138
	s_nop 1
	v_permlane32_swap_b32_e32 v138, v139
	v_max_f32_e32 v186, v138, v139
	v_cmp_gt_f32_e32 vcc, v186, v1
	s_cbranch_vccz .LBB0_945
	v_max_f32_e32 v138, v186, v186
	v_max_f32_e32 v139, v220, v220
	v_max_f32_e32 v222, v139, v138
	v_cmp_neq_f32_e32 vcc, s81, v222
	v_mov_b32_e32 v223, v221
	v_mov_b32_e32 v225, v219
	v_cndmask_b32_e32 v138, 0, v222, vcc
	v_sub_f32_e32 v138, v220, v138
	v_mul_f32_e32 v138, 0x3e16c740, v138
	v_exp_f32_e32 v138, v138
	v_mov_b32_e32 v187, v222
	v_mul_f32_e32 v224, v218, v138
	v_pk_mul_f32 v[92:93], v[92:93], v[138:139] op_sel_hi:[1,0]
	v_pk_mul_f32 v[90:91], v[90:91], v[138:139] op_sel_hi:[1,0]
	v_pk_mul_f32 v[88:89], v[88:89], v[138:139] op_sel_hi:[1,0]
	v_pk_mul_f32 v[86:87], v[86:87], v[138:139] op_sel_hi:[1,0]
	v_pk_mul_f32 v[76:77], v[76:77], v[138:139] op_sel_hi:[1,0]
	v_pk_mul_f32 v[74:75], v[74:75], v[138:139] op_sel_hi:[1,0]
	v_pk_mul_f32 v[68:69], v[68:69], v[138:139] op_sel_hi:[1,0]
	v_pk_mul_f32 v[66:67], v[66:67], v[138:139] op_sel_hi:[1,0]

; __device__ __forceinline__ float ex2(float x) { return __builtin_amdgcn_exp2f(x); }
; __device__ __forceinline__ f32x4 mfma16(bf16x8 a, bf16x8 b, f32x4 c) { return __builtin_amdgcn_mfma_f32_16x16x32_bf16(a, b, c, 0, 0, 0); }
; __device__ __forceinline__ s16x4 ds_tr(LAS const unsigned char* p) { return __builtin_bit_cast(s16x4, __builtin_amdgcn_ds_read_tr16_b64_v4i16((LAS v4i16_t*)p)); }
; template <int NT, int NKK, int NDT, int MODE, bool MASK> ...
;     ...
;     const float mc = ((m[j] == -INFINITY) ? 0.f : m[j]) * c;
;     float p[4][4], ps = 0.f;
; #pragma unroll
;     for (int t = 0; t < 4; ++t)
; #pragma unroll
;       for (int i = 0; i < 4; ++i) { p[t][i] = ex2(s[j][t][i] * c - mc); ps += p[t][i]; }
;     l[j] += ps;
;     pf[j][0] = pack8(p[0], p[1]); pf[j][1] = pack8(p[2], p[3]);
;   }
;   __builtin_amdgcn_s_setprio(1);
; #pragma unroll
;   for (int st = 0; st < 2; ++st)
; #pragma unroll
;     for (int dt = 0; dt < NDT; ++dt) {
;       const s16x4 v0 = ds_tr(Vl + (32 * st + 4 * lg + vq) * VSTR + (16 * dt + 4 * vp) * 2);
;       const s16x4 v1 = ds_tr(Vl + (32 * st + 16 + 4 * lg + vq) * VSTR + (16 * dt + 4 * vp) * 2);
;       const bf16x8 vf = (bf16x8){v0[0], v0[1], v0[2], v0[3], v1[0], v1[1], v1[2], v1[3]};
; #pragma unroll
;       for (int j = 0; j < NT; ++j) o[j][dt] = mfma16(vf, pf[j][st], o[j][dt]);
;     }
;   __builtin_amdgcn_s_setprio(0);
.LBB0_960:
	v_cvt_pk_bf16_f32 v173, v196, v173
	v_mul_f32_e32 v196, 0x3e16c740, v197
	v_cmp_neq_f32_e32 vcc, s81, v197
	v_cvt_pk_bf16_f32 v172, v232, v228
	v_cvt_pk_bf16_f32 v228, v205, v207
	v_cndmask_b32_e32 v196, 0, v196, vcc
	v_fma_f32 v166, v166, s88, -v196
	v_exp_f32_e32 v166, v166
	v_fma_f32 v167, v167, s88, -v196
	v_exp_f32_e32 v167, v167
	v_fma_f32 v168, v168, s88, -v196
	v_exp_f32_e32 v168, v168
	v_fma_f32 v169, v169, s88, -v196
	v_exp_f32_e32 v169, v169
	v_fma_f32 v154, v154, s88, -v196
	v_exp_f32_e32 v154, v154
	v_fma_f32 v155, v155, s88, -v196
	v_add_f32_e32 v197, v167, v166
	v_exp_f32_e32 v155, v155
	v_fma_f32 v156, v156, s88, -v196
	v_add_f32_e32 v197, v168, v197
	v_exp_f32_e32 v156, v156
	v_fma_f32 v157, v157, s88, -v196
	v_add_f32_e32 v197, v169, v197
	v_exp_f32_e32 v157, v157
	v_fma_f32 v150, v150, s88, -v196
	v_add_f32_e32 v197, v154, v197
	v_exp_f32_e32 v150, v150
	v_fma_f32 v151, v151, s88, -v196
	v_add_f32_e32 v197, v155, v197
	v_exp_f32_e32 v151, v151
	v_fma_f32 v152, v152, s88, -v196
	v_add_f32_e32 v197, v156, v197
	v_exp_f32_e32 v152, v152
	v_fma_f32 v153, v153, s88, -v196
	v_add_f32_e32 v197, v157, v197
	v_exp_f32_e32 v153, v153
	v_fma_f32 v142, v142, s88, -v196
	v_add_f32_e32 v197, v150, v197
	v_exp_f32_e32 v198, v142
	v_fma_f32 v142, v143, s88, -v196
	v_add_f32_e32 v197, v151, v197
	v_exp_f32_e32 v199, v142
	v_fma_f32 v142, v144, s88, -v196
	v_add_f32_e32 v197, v152, v197
	v_exp_f32_e32 v205, v142
	v_fma_f32 v142, v145, s88, -v196
	v_add_f32_e32 v197, v153, v197
	v_exp_f32_e32 v196, v142
	v_add_f32_e32 v142, v198, v197
	v_add_f32_e32 v142, v199, v142
	v_add_f32_e32 v142, v205, v142
	v_add_f32_e32 v142, v196, v142
	v_add_f32_e32 v225, v225, v142
	v_cvt_pk_bf16_f32 v142, v166, v167
	v_cvt_pk_bf16_f32 v143, v168, v169
	v_cvt_pk_bf16_f32 v144, v154, v155
	v_cvt_pk_bf16_f32 v145, v156, v157
	v_cvt_pk_bf16_f32 v170, v252, v231
	v_cvt_pk_bf16_f32 v171, v229, v230
	v_cvt_pk_bf16_f32 v229, v246, v247
	v_cvt_pk_bf16_f32 v230, v248, v249
	v_cvt_pk_bf16_f32 v231, v250, v251
	v_cvt_pk_bf16_f32 v246, v150, v151
	v_cvt_pk_bf16_f32 v247, v152, v153
	v_cvt_pk_bf16_f32 v248, v198, v199
	v_cvt_pk_bf16_f32 v249, v205, v196
	s_setprio 1
	v_add3_u32 v196, s45, v240, v239
	ds_read_b64_tr_b16 v[152:153], v196 offset:15872
	ds_read_b64_tr_b16 v[150:151], v196 offset:13312
	ds_read_b64_tr_b16 v[154:155], v196 offset:13344
	ds_read_b64_tr_b16 v[156:157], v196 offset:15904
	ds_read_b64_tr_b16 v[166:167], v196 offset:13376
	ds_read_b64_tr_b16 v[168:169], v196 offset:15936
	s_mov_b64 s[20:21], 0
	s_waitcnt lgkmcnt(4)
	v_mfma_f32_16x16x32_bf16 v[158:161], v[150:153], v[228:231], v[90:93]
	v_mfma_f32_16x16x32_bf16 v[150:153], v[150:153], v[142:145], v[82:85]
	v_mov_b64_e32 v[218:219], v[224:225]
	s_waitcnt lgkmcnt(0)
	v_mfma_f32_16x16x32_bf16 v[182:185], v[166:169], v[228:231], v[74:77]
	s_nop 2
	ds_read_b64_tr_b16 v[146:147], v196 offset:13408
	ds_read_b64_tr_b16 v[148:149], v196 offset:15968
	v_mfma_f32_16x16x32_bf16 v[162:165], v[154:157], v[228:231], v[86:89]
	v_mov_b64_e32 v[220:221], v[222:223]
	v_mfma_f32_16x16x32_bf16 v[154:157], v[154:157], v[142:145], v[78:81]
	v_mfma_f32_16x16x32_bf16 v[166:169], v[166:169], v[142:145], v[70:73]
	s_waitcnt lgkmcnt(0)
	v_mfma_f32_16x16x32_bf16 v[174:177], v[146:149], v[142:145], v[62:65]
	ds_read_b64_tr_b16 v[142:143], v196 offset:18432
	ds_read_b64_tr_b16 v[144:145], v196 offset:20992
	v_mfma_f32_16x16x32_bf16 v[178:181], v[146:149], v[228:231], v[66:69]
	s_waitcnt lgkmcnt(0)
	v_mfma_f32_16x16x32_bf16 v[90:93], v[142:145], v[170:173], v[158:161]
	v_mfma_f32_16x16x32_bf16 v[82:85], v[142:145], v[246:249], v[150:153]
	s_nop 2
	ds_read_b64_tr_b16 v[150:151], v196 offset:18464
	ds_read_b64_tr_b16 v[152:153], v196 offset:21024
	ds_read_b64_tr_b16 v[158:159], v196 offset:18496
	ds_read_b64_tr_b16 v[160:161], v196 offset:21056
	s_waitcnt lgkmcnt(2)
	v_mfma_f32_16x16x32_bf16 v[86:89], v[150:153], v[170:173], v[162:165]
	s_nop 2
	ds_read_b64_tr_b16 v[162:163], v196 offset:18528
	ds_read_b64_tr_b16 v[164:165], v196 offset:21088
	v_mfma_f32_16x16x32_bf16 v[78:81], v[150:153], v[246:249], v[154:157]
	s_waitcnt lgkmcnt(2)
	v_mfma_f32_16x16x32_bf16 v[74:77], v[158:161], v[170:173], v[182:185]
	v_mfma_f32_16x16x32_bf16 v[70:73], v[158:161], v[246:249], v[166:169]
	s_waitcnt lgkmcnt(0)
	v_mfma_f32_16x16x32_bf16 v[66:69], v[162:165], v[170:173], v[178:181]
	v_mfma_f32_16x16x32_bf16 v[62:65], v[162:165], v[246:249], v[174:177]
	s_setprio 0
	s_branch .LBB0_970

; #define LAS __attribute__((address_space(3)))
; __device__ __forceinline__ float ex2(float x) { return __builtin_amdgcn_exp2f(x); }
; #define LBAR() asm volatile("s_waitcnt lgkmcnt(0)\n\ts_barrier" ::: "memory")
; template <int NT, int NKK, int NDT, int MODE, bool MASK> ...
;   const int r = lane & 15, lg = lane >> 4, vq = (lane & 15) >> 2, vp = lane & 3;
;   f32x4 s[NT][4];
;   __builtin_amdgcn_s_setprio(1);
; #pragma unroll
;   for (int t = 0; t < 4; ++t)
; #pragma unroll
;     for (int kk = 0; kk < NKK; ++kk) {
;       const bf16x8 kf = *(LAS const bf16x8*)(Kl + (16 * t + r) * KSTR + (32 * kk + 8 * lg) * 2);
; #pragma unroll
;       for (int j = 0; j < NT; ++j) s[j][t] = mfma16(kf, qf[j][kk], kk == 0 ? (f32x4){0.f, 0.f, 0.f, 0.f} : s[j][t]);
;     }
;   __builtin_amdgcn_s_setprio(0);
;   bf16x8 pf[NT][2];
; #pragma unroll
;   for (int j = 0; j < NT; ++j) {
;     float mx = -INFINITY;
; #pragma unroll
;     for (int t = 0; t < 4; ++t)
; #pragma unroll
;       for (int i = 0; i < 4; ++i) {
;         if (MASK) { const int kp = kpos0 + 16 * t + 4 * lg + i; if (!mask_ok<MODE>(tq[j], kp, W)) s[j][t][i] = -INFINITY; }
;         mx = fmaxf(mx, s[j][t][i]);
;       }
;     mx = max_x16_x32(mx);
;     if (__any(mx > m[j] + 8.0f / c)) {
;       const float mnew = fmaxf(m[j], mx);
;       const float ms2 = (mnew == -INFINITY) ? 0.f : mnew;
;       const float alpha = ex2((m[j] - ms2) * c);
;       m[j] = mnew; l[j] *= alpha;
; #pragma unroll
;       for (int dt = 0; dt < NDT; ++dt) o[j][dt] *= alpha;
;     }
; template <int NT, int DQK, int DV, int MODE, int PD, class Src> ...
;     ...
;         LBAR();
;         const int lo = kbase + 64 * kc, hi = lo + 63;
;         bool rel = true, full = true;
;         if (MODE == MODE_CAUSAL) { rel = lo <= tq_max; full = hi <= tq_min; }
;         if (MODE == MODE_WINDOW) { rel = (lo <= tq_max) && (hi > tq_min - W); full = (hi <= tq_min) && (lo > tq_max - W); }
;         if (MODE == MODE_CMP) { rel = 16 * lo + 31 <= tq_max; full = 16 * hi + 31 <= tq_min; }
;         if (rel) {
;           if (NT <= 2) {
;             if (full) attn_chunk_wide<NT, DQK / 32, DV / 16, MODE, false>(o, m, l, qf, buf, KSTR, buf + KB, VSTR, lo, tq, c, W, lane);
;             else attn_chunk_wide<NT, DQK / 32, DV / 16, MODE, true>(o, m, l, qf, buf, KSTR, buf + KB, VSTR, lo, tq, c, W, lane);
.LBB0_983:
	s_waitcnt lgkmcnt(0)
	s_barrier
	s_add_i32 s8, s43, 0xffffff81
	s_cmp_gt_i32 s8, s40
	s_cbranch_scc1 .LBB0_1010
	s_sub_i32 s8, s43, 64
	s_cmp_gt_i32 s8, s25
	s_setprio 1
	v_add_u32_e32 v1, s59, v236
	s_waitcnt lgkmcnt(0)
	v_add_u32_e32 v94, v1, v237
	ds_read_b128 v[134:137], v94
	ds_read_b128 v[130:133], v94 offset:64
	ds_read_b128 v[126:129], v94 offset:128
	ds_read_b128 v[122:125], v94 offset:3328
	ds_read_b128 v[118:121], v94 offset:3392
	ds_read_b128 v[114:117], v94 offset:3456
	ds_read_b128 v[106:109], v94 offset:6656
	ds_read_b128 v[98:101], v94 offset:6720
	v_add_u32_e32 v201, v1, v238
	ds_read_b128 v[110:113], v94 offset:6784
	ds_read_b128 v[102:105], v201
	ds_read_b128 v[94:97], v201 offset:64
	s_mov_b64 s[20:21], -1
	v_add_f32_e32 v1, 0x4259535f, v220
	s_cbranch_scc1 .LBB0_1001
	s_waitcnt lgkmcnt(10)
	v_mfma_f32_16x16x32_bf16 v[138:141], v[134:137], v[18:21], 0
	ds_read_b128 v[146:149], v201 offset:128
	v_mov_b32_e32 v234, 0x260
	v_mfma_f32_16x16x32_bf16 v[142:145], v[134:137], v[10:13], 0
	s_waitcnt lgkmcnt(10)
	v_mfma_f32_16x16x32_bf16 v[138:141], v[130:133], v[2:5], v[138:141]
	v_mov_b64_e32 v[222:223], v[220:221]
	v_mfma_f32_16x16x32_bf16 v[142:145], v[130:133], v[14:17], v[142:145]
	v_mov_b64_e32 v[224:225], v[218:219]
	s_waitcnt lgkmcnt(9)
	v_mfma_f32_16x16x32_bf16 v[182:185], v[126:129], v[6:9], v[138:141]
	v_mfma_f32_16x16x32_bf16 v[166:169], v[126:129], v[22:25], v[142:145]
	v_mov_b32_e32 v187, v220
	s_waitcnt lgkmcnt(8)
	v_mfma_f32_16x16x32_bf16 v[138:141], v[122:125], v[18:21], 0
	v_mfma_f32_16x16x32_bf16 v[142:145], v[122:125], v[10:13], 0
	s_waitcnt lgkmcnt(7)
	v_mfma_f32_16x16x32_bf16 v[138:141], v[118:121], v[2:5], v[138:141]
	v_mfma_f32_16x16x32_bf16 v[142:145], v[118:121], v[14:17], v[142:145]
	s_waitcnt lgkmcnt(6)
	v_mfma_f32_16x16x32_bf16 v[178:181], v[114:117], v[6:9], v[138:141]
	v_mfma_f32_16x16x32_bf16 v[154:157], v[114:117], v[22:25], v[142:145]
	s_waitcnt lgkmcnt(5)
	v_mfma_f32_16x16x32_bf16 v[138:141], v[106:109], v[18:21], 0
	v_mfma_f32_16x16x32_bf16 v[142:145], v[106:109], v[10:13], 0
	v_max3_f32 v188, v182, s81, v183
	s_waitcnt lgkmcnt(4)
	v_mfma_f32_16x16x32_bf16 v[138:141], v[98:101], v[2:5], v[138:141]
	v_max3_f32 v188, v188, v184, v185
	v_mfma_f32_16x16x32_bf16 v[142:145], v[98:101], v[14:17], v[142:145]
	v_max3_f32 v189, v166, s81, v167
	s_waitcnt lgkmcnt(3)
	v_mfma_f32_16x16x32_bf16 v[174:177], v[110:113], v[6:9], v[138:141]
	v_max3_f32 v189, v189, v168, v169
	v_mfma_f32_16x16x32_bf16 v[150:153], v[110:113], v[22:25], v[142:145]
	s_waitcnt lgkmcnt(2)
	v_mfma_f32_16x16x32_bf16 v[138:141], v[102:105], v[18:21], 0
	v_mfma_f32_16x16x32_bf16 v[142:145], v[102:105], v[10:13], 0
	v_max3_f32 v188, v188, v178, v179
	s_waitcnt lgkmcnt(1)
	v_mfma_f32_16x16x32_bf16 v[138:141], v[94:97], v[2:5], v[138:141]
	v_max3_f32 v188, v188, v180, v181
	v_mfma_f32_16x16x32_bf16 v[142:145], v[94:97], v[14:17], v[142:145]
	v_max3_f32 v189, v189, v154, v155
	s_waitcnt lgkmcnt(0)
	v_mfma_f32_16x16x32_bf16 v[170:173], v[146:149], v[6:9], v[138:141]
	v_max3_f32 v189, v189, v156, v157
	v_mfma_f32_16x16x32_bf16 v[142:145], v[146:149], v[22:25], v[142:145]
	s_setprio 0
	s_nop 3
	v_max3_f32 v138, v188, v174, v175
	v_max3_f32 v138, v138, v176, v177
	v_max3_f32 v138, v138, v170, v171
	v_max3_f32 v138, v138, v172, v173
	v_mov_b32_e32 v139, v138
	s_nop 1
	v_permlane16_swap_b32_e32 v138, v139
	v_max_f32_e32 v138, v138, v139
	v_mov_b32_e32 v139, v138
	s_nop 1
	v_permlane32_swap_b32_e32 v138, v139
	v_max_f32_e32 v186, v138, v139
	v_cmp_gt_f32_e32 vcc, v186, v1
	s_cbranch_vccz .LBB0_987
	v_max_f32_e32 v138, v186, v186
	v_max_f32_e32 v139, v220, v220
	v_max_f32_e32 v222, v139, v138
	v_cmp_neq_f32_e32 vcc, s81, v222
	v_mov_b32_e32 v223, v221
	v_mov_b32_e32 v225, v219
	v_cndmask_b32_e32 v138, 0, v222, vcc
	v_sub_f32_e32 v138, v220, v138
	v_mul_f32_e32 v138, 0x3e16c740, v138
	v_exp_f32_e32 v138, v138
	v_mov_b32_e32 v187, v222
	v_mul_f32_e32 v224, v218, v138
	v_pk_mul_f32 v[92:93], v[92:93], v[138:139] op_sel_hi:[1,0]
	v_pk_mul_f32 v[90:91], v[90:91], v[138:139] op_sel_hi:[1,0]
	v_pk_mul_f32 v[88:89], v[88:89], v[138:139] op_sel_hi:[1,0]
	v_pk_mul_f32 v[86:87], v[86:87], v[138:139] op_sel_hi:[1,0]
	v_pk_mul_f32 v[76:77], v[76:77], v[138:139] op_sel_hi:[1,0]
	v_pk_mul_f32 v[74:75], v[74:75], v[138:139] op_sel_hi:[1,0]
	v_pk_mul_f32 v[68:69], v[68:69], v[138:139] op_sel_hi:[1,0]
	v_pk_mul_f32 v[66:67], v[66:67], v[138:139] op_sel_hi:[1,0]

; __device__ __forceinline__ float ex2(float x) { return __builtin_amdgcn_exp2f(x); }
; __device__ __forceinline__ f32x4 mfma16(bf16x8 a, bf16x8 b, f32x4 c) { return __builtin_amdgcn_mfma_f32_16x16x32_bf16(a, b, c, 0, 0, 0); }
; __device__ __forceinline__ s16x4 ds_tr(LAS const unsigned char* p) { return __builtin_bit_cast(s16x4, __builtin_amdgcn_ds_read_tr16_b64_v4i16((LAS v4i16_t*)p)); }
; template <int NT, int NKK, int NDT, int MODE, bool MASK> ...
;     ...
;     const float mc = ((m[j] == -INFINITY) ? 0.f : m[j]) * c;
;     float p[4][4], ps = 0.f;
; #pragma unroll
;     for (int t = 0; t < 4; ++t)
; #pragma unroll
;       for (int i = 0; i < 4; ++i) { p[t][i] = ex2(s[j][t][i] * c - mc); ps += p[t][i]; }
;     l[j] += ps;
;     pf[j][0] = pack8(p[0], p[1]); pf[j][1] = pack8(p[2], p[3]);
;   }
;   __builtin_amdgcn_s_setprio(1);
; #pragma unroll
;   for (int st = 0; st < 2; ++st)
; #pragma unroll
;     for (int dt = 0; dt < NDT; ++dt) {
;       const s16x4 v0 = ds_tr(Vl + (32 * st + 4 * lg + vq) * VSTR + (16 * dt + 4 * vp) * 2);
;       const s16x4 v1 = ds_tr(Vl + (32 * st + 16 + 4 * lg + vq) * VSTR + (16 * dt + 4 * vp) * 2);
;       const bf16x8 vf = (bf16x8){v0[0], v0[1], v0[2], v0[3], v1[0], v1[1], v1[2], v1[3]};
; #pragma unroll
;       for (int j = 0; j < NT; ++j) o[j][dt] = mfma16(vf, pf[j][st], o[j][dt]);
;     }
;   __builtin_amdgcn_s_setprio(0);
.LBB0_1000:
	v_cvt_pk_bf16_f32 v173, v196, v173
	v_mul_f32_e32 v196, 0x3e16c740, v197
	v_cmp_neq_f32_e32 vcc, s81, v197
	v_cvt_pk_bf16_f32 v172, v232, v228
	v_cvt_pk_bf16_f32 v228, v205, v207
	v_cndmask_b32_e32 v196, 0, v196, vcc
	v_fma_f32 v166, v166, s88, -v196
	v_exp_f32_e32 v166, v166
	v_fma_f32 v167, v167, s88, -v196
	v_exp_f32_e32 v167, v167
	v_fma_f32 v168, v168, s88, -v196
	v_exp_f32_e32 v168, v168
	v_fma_f32 v169, v169, s88, -v196
	v_exp_f32_e32 v169, v169
	v_fma_f32 v154, v154, s88, -v196
	v_exp_f32_e32 v154, v154
	v_fma_f32 v155, v155, s88, -v196
	v_add_f32_e32 v197, v167, v166
	v_exp_f32_e32 v155, v155
	v_fma_f32 v156, v156, s88, -v196
	v_add_f32_e32 v197, v168, v197
	v_exp_f32_e32 v156, v156
	v_fma_f32 v157, v157, s88, -v196
	v_add_f32_e32 v197, v169, v197
	v_exp_f32_e32 v157, v157
	v_fma_f32 v150, v150, s88, -v196
	v_add_f32_e32 v197, v154, v197
	v_exp_f32_e32 v150, v150
	v_fma_f32 v151, v151, s88, -v196
	v_add_f32_e32 v197, v155, v197
	v_exp_f32_e32 v151, v151
	v_fma_f32 v152, v152, s88, -v196
	v_add_f32_e32 v197, v156, v197
	v_exp_f32_e32 v152, v152
	v_fma_f32 v153, v153, s88, -v196
	v_add_f32_e32 v197, v157, v197
	v_exp_f32_e32 v153, v153
	v_fma_f32 v142, v142, s88, -v196
	v_add_f32_e32 v197, v150, v197
	v_exp_f32_e32 v198, v142
	v_fma_f32 v142, v143, s88, -v196
	v_add_f32_e32 v197, v151, v197
	v_exp_f32_e32 v199, v142
	v_fma_f32 v142, v144, s88, -v196
	v_add_f32_e32 v197, v152, v197
	v_exp_f32_e32 v205, v142
	v_fma_f32 v142, v145, s88, -v196
	v_add_f32_e32 v197, v153, v197
	v_exp_f32_e32 v196, v142
	v_add_f32_e32 v142, v198, v197
	v_add_f32_e32 v142, v199, v142
	v_add_f32_e32 v142, v205, v142
	v_add_f32_e32 v142, v196, v142
	v_add_f32_e32 v225, v225, v142
	v_cvt_pk_bf16_f32 v142, v166, v167
	v_cvt_pk_bf16_f32 v143, v168, v169
	v_cvt_pk_bf16_f32 v144, v154, v155
	v_cvt_pk_bf16_f32 v145, v156, v157
	v_cvt_pk_bf16_f32 v170, v252, v231
	v_cvt_pk_bf16_f32 v171, v229, v230
	v_cvt_pk_bf16_f32 v229, v246, v247
	v_cvt_pk_bf16_f32 v230, v248, v249
	v_cvt_pk_bf16_f32 v231, v250, v251
	v_cvt_pk_bf16_f32 v246, v150, v151
	v_cvt_pk_bf16_f32 v247, v152, v153
	v_cvt_pk_bf16_f32 v248, v198, v199
	v_cvt_pk_bf16_f32 v249, v205, v196
	s_setprio 1
	v_add3_u32 v196, s59, v240, v239
	ds_read_b64_tr_b16 v[152:153], v196 offset:15872
	ds_read_b64_tr_b16 v[150:151], v196 offset:13312
	ds_read_b64_tr_b16 v[154:155], v196 offset:13344
	ds_read_b64_tr_b16 v[156:157], v196 offset:15904
	ds_read_b64_tr_b16 v[166:167], v196 offset:13376
	ds_read_b64_tr_b16 v[168:169], v196 offset:15936
	s_mov_b64 s[20:21], 0
	s_waitcnt lgkmcnt(4)
	v_mfma_f32_16x16x32_bf16 v[158:161], v[150:153], v[228:231], v[90:93]
	v_mfma_f32_16x16x32_bf16 v[150:153], v[150:153], v[142:145], v[82:85]
	v_mov_b64_e32 v[218:219], v[224:225]
	s_waitcnt lgkmcnt(0)
	v_mfma_f32_16x16x32_bf16 v[182:185], v[166:169], v[228:231], v[74:77]
	s_nop 2
	ds_read_b64_tr_b16 v[146:147], v196 offset:13408
	ds_read_b64_tr_b16 v[148:149], v196 offset:15968
	v_mfma_f32_16x16x32_bf16 v[162:165], v[154:157], v[228:231], v[86:89]
	v_mov_b64_e32 v[220:221], v[222:223]
	v_mfma_f32_16x16x32_bf16 v[154:157], v[154:157], v[142:145], v[78:81]
	v_mfma_f32_16x16x32_bf16 v[166:169], v[166:169], v[142:145], v[70:73]
	s_waitcnt lgkmcnt(0)
	v_mfma_f32_16x16x32_bf16 v[174:177], v[146:149], v[142:145], v[62:65]
	ds_read_b64_tr_b16 v[142:143], v196 offset:18432
	ds_read_b64_tr_b16 v[144:145], v196 offset:20992
	v_mfma_f32_16x16x32_bf16 v[178:181], v[146:149], v[228:231], v[66:69]
	s_waitcnt lgkmcnt(0)
	v_mfma_f32_16x16x32_bf16 v[90:93], v[142:145], v[170:173], v[158:161]
	v_mfma_f32_16x16x32_bf16 v[82:85], v[142:145], v[246:249], v[150:153]
	s_nop 2
	ds_read_b64_tr_b16 v[150:151], v196 offset:18464
	ds_read_b64_tr_b16 v[152:153], v196 offset:21024
	ds_read_b64_tr_b16 v[158:159], v196 offset:18496
	ds_read_b64_tr_b16 v[160:161], v196 offset:21056
	s_waitcnt lgkmcnt(2)
	v_mfma_f32_16x16x32_bf16 v[86:89], v[150:153], v[170:173], v[162:165]
	s_nop 2
	ds_read_b64_tr_b16 v[162:163], v196 offset:18528
	ds_read_b64_tr_b16 v[164:165], v196 offset:21088
	v_mfma_f32_16x16x32_bf16 v[78:81], v[150:153], v[246:249], v[154:157]
	s_waitcnt lgkmcnt(2)
	v_mfma_f32_16x16x32_bf16 v[74:77], v[158:161], v[170:173], v[182:185]
	v_mfma_f32_16x16x32_bf16 v[70:73], v[158:161], v[246:249], v[166:169]
	s_waitcnt lgkmcnt(0)
	v_mfma_f32_16x16x32_bf16 v[66:69], v[162:165], v[170:173], v[178:181]
	v_mfma_f32_16x16x32_bf16 v[62:65], v[162:165], v[246:249], v[174:177]
	s_setprio 0
	s_branch .LBB0_1010

; #define LAS __attribute__((address_space(3)))
; __device__ __forceinline__ float ex2(float x) { return __builtin_amdgcn_exp2f(x); }
; #define LBAR() asm volatile("s_waitcnt lgkmcnt(0)\n\ts_barrier" ::: "memory")
; template <int NT, int NKK, int NDT, int MODE, bool MASK> ...
;   const int r = lane & 15, lg = lane >> 4, vq = (lane & 15) >> 2, vp = lane & 3;
;   f32x4 s[NT][4];
;   __builtin_amdgcn_s_setprio(1);
; #pragma unroll
;   for (int t = 0; t < 4; ++t)
; #pragma unroll
;     for (int kk = 0; kk < NKK; ++kk) {
;       const bf16x8 kf = *(LAS const bf16x8*)(Kl + (16 * t + r) * KSTR + (32 * kk + 8 * lg) * 2);
; #pragma unroll
;       for (int j = 0; j < NT; ++j) s[j][t] = mfma16(kf, qf[j][kk], kk == 0 ? (f32x4){0.f, 0.f, 0.f, 0.f} : s[j][t]);
;     }
;   __builtin_amdgcn_s_setprio(0);
;   bf16x8 pf[NT][2];
; #pragma unroll
;   for (int j = 0; j < NT; ++j) {
;     float mx = -INFINITY;
; #pragma unroll
;     for (int t = 0; t < 4; ++t)
; #pragma unroll
;       for (int i = 0; i < 4; ++i) {
;         if (MASK) { const int kp = kpos0 + 16 * t + 4 * lg + i; if (!mask_ok<MODE>(tq[j], kp, W)) s[j][t][i] = -INFINITY; }
;         mx = fmaxf(mx, s[j][t][i]);
;       }
;     mx = max_x16_x32(mx);
;     if (__any(mx > m[j] + 8.0f / c)) {
;       const float mnew = fmaxf(m[j], mx);
;       const float ms2 = (mnew == -INFINITY) ? 0.f : mnew;
;       const float alpha = ex2((m[j] - ms2) * c);
;       m[j] = mnew; l[j] *= alpha;
; #pragma unroll
;       for (int dt = 0; dt < NDT; ++dt) o[j][dt] *= alpha;
;     }
; template <int NT, int DQK, int DV, int MODE, int PD, class Src> ...
;     ...
;         LBAR();
;         const int lo = kbase + 64 * kc, hi = lo + 63;
;         bool rel = true, full = true;
;         if (MODE == MODE_CAUSAL) { rel = lo <= tq_max; full = hi <= tq_min; }
;         if (MODE == MODE_WINDOW) { rel = (lo <= tq_max) && (hi > tq_min - W); full = (hi <= tq_min) && (lo > tq_max - W); }
;         if (MODE == MODE_CMP) { rel = 16 * lo + 31 <= tq_max; full = 16 * hi + 31 <= tq_min; }
;         if (rel) {
;           if (NT <= 2) {
;             if (full) attn_chunk_wide<NT, DQK / 32, DV / 16, MODE, false>(o, m, l, qf, buf, KSTR, buf + KB, VSTR, lo, tq, c, W, lane);
;             else attn_chunk_wide<NT, DQK / 32, DV / 16, MODE, true>(o, m, l, qf, buf, KSTR, buf + KB, VSTR, lo, tq, c, W, lane);
.LBB0_1023:
	s_waitcnt lgkmcnt(0)
	s_barrier
	s_sub_i32 s8, s43, 63
	s_cmp_gt_i32 s8, s40
	s_cbranch_scc1 .LBB0_1050
	s_cmp_gt_i32 s43, s25
	s_setprio 1
	v_add_u32_e32 v1, s45, v236
	s_waitcnt lgkmcnt(0)
	v_add_u32_e32 v94, v1, v237
	ds_read_b128 v[134:137], v94
	ds_read_b128 v[130:133], v94 offset:64
	ds_read_b128 v[126:129], v94 offset:128
	ds_read_b128 v[122:125], v94 offset:3328
	ds_read_b128 v[118:121], v94 offset:3392
	ds_read_b128 v[114:117], v94 offset:3456
	ds_read_b128 v[106:109], v94 offset:6656
	ds_read_b128 v[98:101], v94 offset:6720
	v_add_u32_e32 v201, v1, v238
	ds_read_b128 v[110:113], v94 offset:6784
	ds_read_b128 v[102:105], v201
	ds_read_b128 v[94:97], v201 offset:64
	s_mov_b64 s[20:21], -1
	v_add_f32_e32 v1, 0x4259535f, v220
	s_cbranch_scc1 .LBB0_1041
	s_waitcnt lgkmcnt(10)
	v_mfma_f32_16x16x32_bf16 v[138:141], v[134:137], v[18:21], 0
	ds_read_b128 v[146:149], v201 offset:128
	v_mov_b32_e32 v234, 0x260
	v_mfma_f32_16x16x32_bf16 v[142:145], v[134:137], v[10:13], 0
	s_waitcnt lgkmcnt(10)
	v_mfma_f32_16x16x32_bf16 v[138:141], v[130:133], v[2:5], v[138:141]
	v_mov_b64_e32 v[222:223], v[220:221]
	v_mfma_f32_16x16x32_bf16 v[142:145], v[130:133], v[14:17], v[142:145]
	v_mov_b64_e32 v[224:225], v[218:219]
	s_waitcnt lgkmcnt(9)
	v_mfma_f32_16x16x32_bf16 v[182:185], v[126:129], v[6:9], v[138:141]
	v_mfma_f32_16x16x32_bf16 v[166:169], v[126:129], v[22:25], v[142:145]
	v_mov_b32_e32 v187, v220
	s_waitcnt lgkmcnt(8)
	v_mfma_f32_16x16x32_bf16 v[138:141], v[122:125], v[18:21], 0
	v_mfma_f32_16x16x32_bf16 v[142:145], v[122:125], v[10:13], 0
	s_waitcnt lgkmcnt(7)
	v_mfma_f32_16x16x32_bf16 v[138:141], v[118:121], v[2:5], v[138:141]
	v_mfma_f32_16x16x32_bf16 v[142:145], v[118:121], v[14:17], v[142:145]
	s_waitcnt lgkmcnt(6)
	v_mfma_f32_16x16x32_bf16 v[178:181], v[114:117], v[6:9], v[138:141]
	v_mfma_f32_16x16x32_bf16 v[154:157], v[114:117], v[22:25], v[142:145]
	s_waitcnt lgkmcnt(5)
	v_mfma_f32_16x16x32_bf16 v[138:141], v[106:109], v[18:21], 0
	v_mfma_f32_16x16x32_bf16 v[142:145], v[106:109], v[10:13], 0
	v_max3_f32 v188, v182, s81, v183
	s_waitcnt lgkmcnt(4)
	v_mfma_f32_16x16x32_bf16 v[138:141], v[98:101], v[2:5], v[138:141]
	v_max3_f32 v188, v188, v184, v185
	v_mfma_f32_16x16x32_bf16 v[142:145], v[98:101], v[14:17], v[142:145]
	v_max3_f32 v189, v166, s81, v167
	s_waitcnt lgkmcnt(3)
	v_mfma_f32_16x16x32_bf16 v[174:177], v[110:113], v[6:9], v[138:141]
	v_max3_f32 v189, v189, v168, v169
	v_mfma_f32_16x16x32_bf16 v[150:153], v[110:113], v[22:25], v[142:145]
	s_waitcnt lgkmcnt(2)
	v_mfma_f32_16x16x32_bf16 v[138:141], v[102:105], v[18:21], 0
	v_mfma_f32_16x16x32_bf16 v[142:145], v[102:105], v[10:13], 0
	v_max3_f32 v188, v188, v178, v179
	s_waitcnt lgkmcnt(1)
	v_mfma_f32_16x16x32_bf16 v[138:141], v[94:97], v[2:5], v[138:141]
	v_max3_f32 v188, v188, v180, v181
	v_mfma_f32_16x16x32_bf16 v[142:145], v[94:97], v[14:17], v[142:145]
	v_max3_f32 v189, v189, v154, v155
	s_waitcnt lgkmcnt(0)
	v_mfma_f32_16x16x32_bf16 v[170:173], v[146:149], v[6:9], v[138:141]
	v_max3_f32 v189, v189, v156, v157
	v_mfma_f32_16x16x32_bf16 v[142:145], v[146:149], v[22:25], v[142:145]
	s_setprio 0
	s_nop 3
	v_max3_f32 v138, v188, v174, v175
	v_max3_f32 v138, v138, v176, v177
	v_max3_f32 v138, v138, v170, v171
	v_max3_f32 v138, v138, v172, v173
	v_mov_b32_e32 v139, v138
	s_nop 1
	v_permlane16_swap_b32_e32 v138, v139
	v_max_f32_e32 v138, v138, v139
	v_mov_b32_e32 v139, v138
	s_nop 1
	v_permlane32_swap_b32_e32 v138, v139
	v_max_f32_e32 v186, v138, v139
	v_cmp_gt_f32_e32 vcc, v186, v1
	s_cbranch_vccz .LBB0_1027
	v_max_f32_e32 v138, v186, v186
	v_max_f32_e32 v139, v220, v220
	v_max_f32_e32 v222, v139, v138
	v_cmp_neq_f32_e32 vcc, s81, v222
	v_mov_b32_e32 v223, v221
	v_mov_b32_e32 v225, v219
	v_cndmask_b32_e32 v138, 0, v222, vcc
	v_sub_f32_e32 v138, v220, v138
	v_mul_f32_e32 v138, 0x3e16c740, v138
	v_exp_f32_e32 v138, v138
	v_mov_b32_e32 v187, v222
	v_mul_f32_e32 v224, v218, v138
	v_pk_mul_f32 v[92:93], v[92:93], v[138:139] op_sel_hi:[1,0]
	v_pk_mul_f32 v[90:91], v[90:91], v[138:139] op_sel_hi:[1,0]
	v_pk_mul_f32 v[88:89], v[88:89], v[138:139] op_sel_hi:[1,0]
	v_pk_mul_f32 v[86:87], v[86:87], v[138:139] op_sel_hi:[1,0]
	v_pk_mul_f32 v[76:77], v[76:77], v[138:139] op_sel_hi:[1,0]
	v_pk_mul_f32 v[74:75], v[74:75], v[138:139] op_sel_hi:[1,0]
	v_pk_mul_f32 v[68:69], v[68:69], v[138:139] op_sel_hi:[1,0]
	v_pk_mul_f32 v[66:67], v[66:67], v[138:139] op_sel_hi:[1,0]
